# P4 rebalanced: bx>=128 convert gate/up before attention with hand-written pipelined conversion; bx<128 attention then hand-written pooling + pool GEMM + w_down conversion
# speedup vs baseline: 1.0194x; 1.0194x over previous
.LBB0_317:
	s_or_b64 exec, exec, s[4:5]
	s_and_b32 s0, s2, 0x80
	s_bitcmp1_b32 s2, 3
	s_cselect_b64 s[6:7], -1, 0
	s_add_u32 s40, s54, 0x1c00000
	s_addc_u32 s41, s55, 0
	s_cmp_eq_u32 s0, 0
	s_waitcnt lgkmcnt(0)
	s_barrier
	s_cbranch_scc1 .LBB0_326
	v_and_b32_e32 v110, 63, v252
	v_lshrrev_b32_e32 v0, 6, v252
	v_writelane_b32 v111, s16, 0
	v_writelane_b32 v111, s17, 1
	v_writelane_b32 v111, s18, 2
	v_writelane_b32 v111, s19, 3
	v_writelane_b32 v111, s20, 4
	v_writelane_b32 v111, s21, 5
	v_writelane_b32 v111, s22, 6
	v_writelane_b32 v111, s23, 7
	v_writelane_b32 v111, s24, 8
	v_writelane_b32 v111, s25, 9
	v_writelane_b32 v111, s26, 10
	v_writelane_b32 v111, s27, 11
	v_readfirstlane_b32 s0, v0
	s_mul_i32 s1, s0, 0x4100
	s_sub_i32 s16, s2, 0x80
	s_lshl_b32 s16, s16, 3
	s_add_u32 s16, s16, s0
	s_cmp_lt_u32 s16, 0x1600
	s_cbranch_scc0 .Lcv_gu_skip
	v_lshrrev_b32_e32 v0, 4, v110
	v_and_b32_e32 v1, 15, v110
	v_and_b32_e32 v2, 7, v110
	v_lshrrev_b32_e32 v3, 3, v110
	v_mul_u32_u24_e32 v64, 0x5800, v0
	v_lshl_add_u32 v64, v1, 4, v64
	v_mul_u32_u24_e32 v65, 0x104, v0
	v_lshl_add_u32 v65, v1, 4, v65
	v_add_u32_e32 v65, s1, v65
	v_mul_u32_u24_e32 v66, 0x820, v2
	v_lshl_add_u32 v66, v3, 2, v66
	v_add_u32_e32 v66, s1, v66
	v_add_u32_e32 v67, 0x410, v66
	v_mul_u32_u24_e32 v68, 0x1000, v3
	v_lshl_add_u32 v68, v2, 4, v68
	v_mov_b32_e32 v4, 0x23fa8
	ds_read_b64 v[0:1], v4
	ds_read_b64 v[2:3], v4 offset:8
	s_waitcnt lgkmcnt(0)
	v_readfirstlane_b32 s18, v0
	v_readfirstlane_b32 s19, v1
	v_readfirstlane_b32 s20, v2
	v_readfirstlane_b32 s21, v3
	s_mov_b32 s26, s40
	s_mov_b32 s27, s41
	s_nop 4
	s_cmp_ge_u32 s16, 0xb00
	s_cselect_b32 s0, 0xb00, 0
	s_cselect_b32 s14, s20, s18
	s_cselect_b32 s15, s21, s19
	s_cselect_b32 s1, 0x10000, 0
	s_sub_u32 s0, s16, s0
	s_mul_hi_u32 s98, s0, 0x2e8ba2f
	s_mul_i32 s99, s98, 0x58
	s_sub_u32 s99, s0, s99
	s_mul_i32 s0, s98, 0x160000
	s_lshl_b32 s100, s99, 8
	s_add_u32 s0, s0, s100
	s_add_u32 s4, s14, s0
	s_addc_u32 s5, s15, 0
	s_lshl_b32 s0, s99, 19
	s_add_u32 s0, s0, s1
	s_lshl_b32 s100, s98, 7
	s_add_u32 s0, s0, s100
	s_add_u32 s24, s26, s0
	s_addc_u32 s25, s27, 0
	global_load_dwordx4 v[0:3], v64, s[4:5] nt
	s_add_u32 s4, s4, 0x16000
	s_addc_u32 s5, s5, 0
	global_load_dwordx4 v[4:7], v64, s[4:5] nt
	s_add_u32 s4, s4, 0x16000
	s_addc_u32 s5, s5, 0
	global_load_dwordx4 v[8:11], v64, s[4:5] nt
	s_add_u32 s4, s4, 0x16000
	s_addc_u32 s5, s5, 0
	global_load_dwordx4 v[12:15], v64, s[4:5] nt
	s_add_u32 s4, s4, 0x16000
	s_addc_u32 s5, s5, 0
	global_load_dwordx4 v[16:19], v64, s[4:5] nt
	s_add_u32 s4, s4, 0x16000
	s_addc_u32 s5, s5, 0
	global_load_dwordx4 v[20:23], v64, s[4:5] nt
	s_add_u32 s4, s4, 0x16000
	s_addc_u32 s5, s5, 0
	global_load_dwordx4 v[24:27], v64, s[4:5] nt
	s_add_u32 s4, s4, 0x16000
	s_addc_u32 s5, s5, 0
	global_load_dwordx4 v[28:31], v64, s[4:5] nt
	s_add_u32 s4, s4, 0x16000
	s_addc_u32 s5, s5, 0
	global_load_dwordx4 v[32:35], v64, s[4:5] nt
	s_add_u32 s4, s4, 0x16000
	s_addc_u32 s5, s5, 0
	global_load_dwordx4 v[36:39], v64, s[4:5] nt
	s_add_u32 s4, s4, 0x16000
	s_addc_u32 s5, s5, 0
	global_load_dwordx4 v[40:43], v64, s[4:5] nt
	s_add_u32 s4, s4, 0x16000
	s_addc_u32 s5, s5, 0
	global_load_dwordx4 v[44:47], v64, s[4:5] nt
	s_add_u32 s4, s4, 0x16000
	s_addc_u32 s5, s5, 0
	global_load_dwordx4 v[48:51], v64, s[4:5] nt
	s_add_u32 s4, s4, 0x16000
	s_addc_u32 s5, s5, 0
	global_load_dwordx4 v[52:55], v64, s[4:5] nt
	s_add_u32 s4, s4, 0x16000
	s_addc_u32 s5, s5, 0
	global_load_dwordx4 v[56:59], v64, s[4:5] nt
	s_add_u32 s4, s4, 0x16000
	s_addc_u32 s5, s5, 0
	global_load_dwordx4 v[60:63], v64, s[4:5] nt
	s_waitcnt vmcnt(0)
	s_branch .Lcv_gu_body

.Lcv_gu_body:
	s_mov_b32 s22, s24
	s_mov_b32 s23, s25
	v_mov_b32_e32 v69, v65
	ds_write2_b32 v69, v0, v1 offset1:1
	ds_write2_b32 v69, v2, v3 offset0:2 offset1:3
	v_add_u32_e32 v69, 0x410, v69
	ds_write2_b32 v69, v4, v5 offset1:1
	ds_write2_b32 v69, v6, v7 offset0:2 offset1:3
	v_add_u32_e32 v69, 0x410, v69
	ds_write2_b32 v69, v8, v9 offset1:1
	ds_write2_b32 v69, v10, v11 offset0:2 offset1:3
	v_add_u32_e32 v69, 0x410, v69
	ds_write2_b32 v69, v12, v13 offset1:1
	ds_write2_b32 v69, v14, v15 offset0:2 offset1:3
	v_add_u32_e32 v69, 0x410, v69
	ds_write2_b32 v69, v16, v17 offset1:1
	ds_write2_b32 v69, v18, v19 offset0:2 offset1:3
	v_add_u32_e32 v69, 0x410, v69
	ds_write2_b32 v69, v20, v21 offset1:1
	ds_write2_b32 v69, v22, v23 offset0:2 offset1:3
	v_add_u32_e32 v69, 0x410, v69
	ds_write2_b32 v69, v24, v25 offset1:1
	ds_write2_b32 v69, v26, v27 offset0:2 offset1:3
	v_add_u32_e32 v69, 0x410, v69
	ds_write2_b32 v69, v28, v29 offset1:1
	ds_write2_b32 v69, v30, v31 offset0:2 offset1:3
	v_add_u32_e32 v69, 0x410, v69
	ds_write2_b32 v69, v32, v33 offset1:1
	ds_write2_b32 v69, v34, v35 offset0:2 offset1:3
	v_add_u32_e32 v69, 0x410, v69
	ds_write2_b32 v69, v36, v37 offset1:1
	ds_write2_b32 v69, v38, v39 offset0:2 offset1:3
	v_add_u32_e32 v69, 0x410, v69
	ds_write2_b32 v69, v40, v41 offset1:1
	ds_write2_b32 v69, v42, v43 offset0:2 offset1:3
	v_add_u32_e32 v69, 0x410, v69
	ds_write2_b32 v69, v44, v45 offset1:1
	ds_write2_b32 v69, v46, v47 offset0:2 offset1:3
	v_add_u32_e32 v69, 0x410, v69
	ds_write2_b32 v69, v48, v49 offset1:1
	ds_write2_b32 v69, v50, v51 offset0:2 offset1:3
	v_add_u32_e32 v69, 0x410, v69
	ds_write2_b32 v69, v52, v53 offset1:1
	ds_write2_b32 v69, v54, v55 offset0:2 offset1:3
	v_add_u32_e32 v69, 0x410, v69
	ds_write2_b32 v69, v56, v57 offset1:1
	ds_write2_b32 v69, v58, v59 offset0:2 offset1:3
	v_add_u32_e32 v69, 0x410, v69
	ds_write2_b32 v69, v60, v61 offset1:1
	ds_write2_b32 v69, v62, v63 offset0:2 offset1:3
	s_waitcnt lgkmcnt(0)
	s_addk_i32 s16, 0x400
	s_cmp_lt_u32 s16, 0x1600
	s_cbranch_scc0 .Lcv_gu_noload
	s_cmp_ge_u32 s16, 0xb00
	s_cselect_b32 s0, 0xb00, 0
	s_cselect_b32 s14, s20, s18
	s_cselect_b32 s15, s21, s19
	s_cselect_b32 s1, 0x10000, 0
	s_sub_u32 s0, s16, s0
	s_mul_hi_u32 s98, s0, 0x2e8ba2f
	s_mul_i32 s99, s98, 0x58
	s_sub_u32 s99, s0, s99
	s_mul_i32 s0, s98, 0x160000
	s_lshl_b32 s100, s99, 8
	s_add_u32 s0, s0, s100
	s_add_u32 s4, s14, s0
	s_addc_u32 s5, s15, 0
	s_lshl_b32 s0, s99, 19
	s_add_u32 s0, s0, s1
	s_lshl_b32 s100, s98, 7
	s_add_u32 s0, s0, s100
	s_add_u32 s24, s26, s0
	s_addc_u32 s25, s27, 0
	global_load_dwordx4 v[0:3], v64, s[4:5] nt
	s_add_u32 s4, s4, 0x16000
	s_addc_u32 s5, s5, 0
	global_load_dwordx4 v[4:7], v64, s[4:5] nt
	s_add_u32 s4, s4, 0x16000
	s_addc_u32 s5, s5, 0
	global_load_dwordx4 v[8:11], v64, s[4:5] nt
	s_add_u32 s4, s4, 0x16000
	s_addc_u32 s5, s5, 0
	global_load_dwordx4 v[12:15], v64, s[4:5] nt
	s_add_u32 s4, s4, 0x16000
	s_addc_u32 s5, s5, 0
	global_load_dwordx4 v[16:19], v64, s[4:5] nt
	s_add_u32 s4, s4, 0x16000
	s_addc_u32 s5, s5, 0
	global_load_dwordx4 v[20:23], v64, s[4:5] nt
	s_add_u32 s4, s4, 0x16000
	s_addc_u32 s5, s5, 0
	global_load_dwordx4 v[24:27], v64, s[4:5] nt
	s_add_u32 s4, s4, 0x16000
	s_addc_u32 s5, s5, 0
	global_load_dwordx4 v[28:31], v64, s[4:5] nt
	s_add_u32 s4, s4, 0x16000
	s_addc_u32 s5, s5, 0
	global_load_dwordx4 v[32:35], v64, s[4:5] nt
	s_add_u32 s4, s4, 0x16000
	s_addc_u32 s5, s5, 0
	global_load_dwordx4 v[36:39], v64, s[4:5] nt
	s_add_u32 s4, s4, 0x16000
	s_addc_u32 s5, s5, 0
	global_load_dwordx4 v[40:43], v64, s[4:5] nt
	s_add_u32 s4, s4, 0x16000
	s_addc_u32 s5, s5, 0
	global_load_dwordx4 v[44:47], v64, s[4:5] nt
	s_add_u32 s4, s4, 0x16000
	s_addc_u32 s5, s5, 0
	global_load_dwordx4 v[48:51], v64, s[4:5] nt
	s_add_u32 s4, s4, 0x16000
	s_addc_u32 s5, s5, 0
	global_load_dwordx4 v[52:55], v64, s[4:5] nt
	s_add_u32 s4, s4, 0x16000
	s_addc_u32 s5, s5, 0
	global_load_dwordx4 v[56:59], v64, s[4:5] nt
	s_add_u32 s4, s4, 0x16000
	s_addc_u32 s5, s5, 0
	global_load_dwordx4 v[60:63], v64, s[4:5] nt
.Lcv_gu_noload:
	s_mov_b32 s8, s22
	s_mov_b32 s9, s23
	ds_read2_b32 v[70:71], v66 offset0:0 offset1:8
	ds_read2_b32 v[72:73], v66 offset0:65 offset1:73
	ds_read2_b32 v[74:75], v66 offset0:130 offset1:138
	ds_read2_b32 v[76:77], v66 offset0:195 offset1:203
	ds_read2_b32 v[78:79], v67 offset0:0 offset1:8
	ds_read2_b32 v[80:81], v67 offset0:65 offset1:73
	ds_read2_b32 v[82:83], v67 offset0:130 offset1:138
	ds_read2_b32 v[84:85], v67 offset0:195 offset1:203
	ds_read2_b32 v[86:87], v66 offset0:16 offset1:24
	ds_read2_b32 v[88:89], v66 offset0:81 offset1:89
	ds_read2_b32 v[90:91], v66 offset0:146 offset1:154
	ds_read2_b32 v[92:93], v66 offset0:211 offset1:219
	ds_read2_b32 v[94:95], v67 offset0:16 offset1:24
	ds_read2_b32 v[96:97], v67 offset0:81 offset1:89
	ds_read2_b32 v[98:99], v67 offset0:146 offset1:154
	ds_read2_b32 v[100:101], v67 offset0:211 offset1:219
	s_waitcnt lgkmcnt(8)
	v_cvt_pk_bf16_f32 v102, v70, v72
	v_cvt_pk_bf16_f32 v103, v74, v76
	v_cvt_pk_bf16_f32 v104, v78, v80
	v_cvt_pk_bf16_f32 v105, v82, v84
	v_cvt_pk_bf16_f32 v106, v71, v73
	v_cvt_pk_bf16_f32 v107, v75, v77
	v_cvt_pk_bf16_f32 v108, v79, v81
	v_cvt_pk_bf16_f32 v109, v83, v85
	global_store_dwordx4 v68, v[102:105], s[8:9]
	s_add_u32 s8, s8, 0x8000
	s_addc_u32 s9, s9, 0
	global_store_dwordx4 v68, v[106:109], s[8:9]
	s_add_u32 s8, s8, 0x18000
	s_addc_u32 s9, s9, 0
	ds_read2_b32 v[70:71], v66 offset0:32 offset1:40
	ds_read2_b32 v[72:73], v66 offset0:97 offset1:105
	ds_read2_b32 v[74:75], v66 offset0:162 offset1:170
	ds_read2_b32 v[76:77], v66 offset0:227 offset1:235
	ds_read2_b32 v[78:79], v67 offset0:32 offset1:40
	ds_read2_b32 v[80:81], v67 offset0:97 offset1:105
	ds_read2_b32 v[82:83], v67 offset0:162 offset1:170
	ds_read2_b32 v[84:85], v67 offset0:227 offset1:235
	s_waitcnt lgkmcnt(8)
	v_cvt_pk_bf16_f32 v102, v86, v88
	v_cvt_pk_bf16_f32 v103, v90, v92
	v_cvt_pk_bf16_f32 v104, v94, v96
	v_cvt_pk_bf16_f32 v105, v98, v100
	v_cvt_pk_bf16_f32 v106, v87, v89
	v_cvt_pk_bf16_f32 v107, v91, v93
	v_cvt_pk_bf16_f32 v108, v95, v97
	v_cvt_pk_bf16_f32 v109, v99, v101
	global_store_dwordx4 v68, v[102:105], s[8:9]
	s_add_u32 s8, s8, 0x8000
	s_addc_u32 s9, s9, 0
	global_store_dwordx4 v68, v[106:109], s[8:9]
	s_add_u32 s8, s8, 0x18000
	s_addc_u32 s9, s9, 0
	ds_read2_b32 v[86:87], v66 offset0:48 offset1:56
	ds_read2_b32 v[88:89], v66 offset0:113 offset1:121
	ds_read2_b32 v[90:91], v66 offset0:178 offset1:186
	ds_read2_b32 v[92:93], v66 offset0:243 offset1:251
	ds_read2_b32 v[94:95], v67 offset0:48 offset1:56
	ds_read2_b32 v[96:97], v67 offset0:113 offset1:121
	ds_read2_b32 v[98:99], v67 offset0:178 offset1:186
	ds_read2_b32 v[100:101], v67 offset0:243 offset1:251
	s_waitcnt lgkmcnt(8)
	v_cvt_pk_bf16_f32 v102, v70, v72
	v_cvt_pk_bf16_f32 v103, v74, v76
	v_cvt_pk_bf16_f32 v104, v78, v80
	v_cvt_pk_bf16_f32 v105, v82, v84
	v_cvt_pk_bf16_f32 v106, v71, v73
	v_cvt_pk_bf16_f32 v107, v75, v77
	v_cvt_pk_bf16_f32 v108, v79, v81
	v_cvt_pk_bf16_f32 v109, v83, v85
	global_store_dwordx4 v68, v[102:105], s[8:9]
	s_add_u32 s8, s8, 0x8000
	s_addc_u32 s9, s9, 0
	global_store_dwordx4 v68, v[106:109], s[8:9]
	s_add_u32 s8, s8, 0x18000
	s_addc_u32 s9, s9, 0
	s_waitcnt lgkmcnt(0)
	v_cvt_pk_bf16_f32 v102, v86, v88
	v_cvt_pk_bf16_f32 v103, v90, v92
	v_cvt_pk_bf16_f32 v104, v94, v96
	v_cvt_pk_bf16_f32 v105, v98, v100
	v_cvt_pk_bf16_f32 v106, v87, v89
	v_cvt_pk_bf16_f32 v107, v91, v93
	v_cvt_pk_bf16_f32 v108, v95, v97
	v_cvt_pk_bf16_f32 v109, v99, v101
	global_store_dwordx4 v68, v[102:105], s[8:9]
	s_add_u32 s8, s8, 0x8000
	s_addc_u32 s9, s9, 0
	global_store_dwordx4 v68, v[106:109], s[8:9]
	s_cmp_lt_u32 s16, 0x1600
	s_cbranch_scc1 .Lcv_gu_top
.Lcv_gu_skip:
	v_readlane_b32 s16, v111, 0
	v_readlane_b32 s17, v111, 1
	v_readlane_b32 s18, v111, 2
	v_readlane_b32 s19, v111, 3
	v_readlane_b32 s20, v111, 4
	v_readlane_b32 s21, v111, 5
	v_readlane_b32 s22, v111, 6
	v_readlane_b32 s23, v111, 7
	v_readlane_b32 s24, v111, 8
	v_readlane_b32 s25, v111, 9
	v_readlane_b32 s26, v111, 10
	v_readlane_b32 s27, v111, 11
	s_nop 4
	s_branch .Lcv_chain_wd
.Lcv_chain_wd:
.LBB0_325:
	s_barrier

.LBB0_437:
.LBB0_446:
	s_xor_b32 s98, s2, 0xff
	s_not_b32 s0, s98
	s_add_i32 s17, s34, s0
	s_cmpk_gt_i32 s17, 0x7f
	s_cbranch_scc1 .LBB0_608
	s_add_u32 s6, s54, 0x13000000
	s_addc_u32 s7, s55, 0
	s_add_u32 s79, s54, 0x5e00000
	s_addc_u32 s80, s55, 0
	s_add_u32 s81, s54, 0x14000800
	v_writelane_b32 v255, s96, 10
	s_addc_u32 s84, s55, 0
	s_xor_b32 s0, s98, 31
	v_writelane_b32 v255, s97, 11
	s_add_i32 s85, s0, s34
	s_xor_b32 s0, s98, 7
	s_add_i32 s86, s0, s34
	v_mov_b32_e32 v145, 0
	s_mov_b32 s49, 0
	s_movk_i32 s91, 0x5000
	v_mov_b32_e32 v253, 0x358637bd
	s_mov_b32 s95, 0xf800000
	v_mov_b32_e32 v254, 0x260
	s_mov_b32 s96, 0x8008000
	s_mov_b32 s97, 0x8010000
	s_mov_b32 s82, 0x8018000
	s_mov_b64 s[50:51], 0x20000
	s_mov_b64 s[52:53], 0x1000
	s_mov_b64 s[56:57], 0x100
	s_add_i32 s9, 0, 0x23f80
	s_movk_i32 s16, 0x600
	s_mov_b64 s[58:59], 0x80
	s_mov_b64 s[60:61], 0x180
	v_writelane_b32 v255, s17, 12
	s_branch .LBB0_449

.LBB0_449:
	s_and_b32 s39, s17, 31
	s_and_b32 s63, s17, 7
	s_ashr_i32 s62, s17, 5
	s_lshl_b32 s38, s39, 8
	s_lshl_b32 s74, s63, 8
	v_and_b32_e32 v125, 31, v252
	v_lshrrev_b32_e32 v126, 5, v252
	v_lshlrev_b32_e32 v127, 4, v125
	v_lshl_add_u32 v121, v126, 16, v127
	v_lshl_add_u32 v122, v126, 14, v127
	s_lshl_b32 s0, s63, 8
	v_lshl_add_u32 v120, v126, 3, s0
	v_mov_b32_e32 v118, 1.0
	s_lshl_b32 s0, s39, 21
	s_lshl_b32 s1, s62, 9
	s_add_u32 s0, s0, s1
	s_add_u32 s0, s0, 0x8001800
	s_add_u32 s68, s54, s0
	s_addc_u32 s69, s55, 0
	s_lshl_b32 s0, s39, 19
	s_add_u32 s0, s0, s1
	s_add_u32 s66, s6, s0
	s_addc_u32 s67, s7, 0
	s_cmp_eq_u32 s62, 0
	s_cbranch_scc1 .Lpl_w2
	s_cmp_eq_u32 s62, 1
	s_cbranch_scc1 .Lpl_w4
	s_cmp_eq_u32 s62, 2
	s_cbranch_scc1 .Lpl_w8
	s_branch .Lpl_w16
.Lpl_w2:
	s_sub_u32 s4, s68, 0x2000
	s_subb_u32 s5, s69, 0
	s_mov_b32 s70, s66
	s_mov_b32 s71, s67
	s_mov_b32 s8, 0
.Lpl_w2_pass:
	global_load_dwordx4 v[0:3], v121, s[4:5]
	s_add_u32 s4, s4, 0x2000
	s_addc_u32 s5, s5, 0
	global_load_dwordx4 v[4:7], v121, s[4:5]
	s_add_u32 s4, s4, 0x2000
	s_addc_u32 s5, s5, 0
	global_load_dwordx4 v[8:11], v121, s[4:5]
	s_add_u32 s4, s4, 0x2000
	s_addc_u32 s5, s5, 0
	global_load_dwordx4 v[12:15], v121, s[4:5]
	s_add_u32 s4, s4, 0x2000
	s_addc_u32 s5, s5, 0
	global_load_dwordx4 v[16:19], v121, s[4:5]
	s_add_u32 s4, s4, 0x2000
	s_addc_u32 s5, s5, 0
	global_load_dwordx4 v[20:23], v121, s[4:5]
	s_add_u32 s4, s4, 0x2000
	s_addc_u32 s5, s5, 0
	global_load_dwordx4 v[24:27], v121, s[4:5]
	s_add_u32 s4, s4, 0x2000
	s_addc_u32 s5, s5, 0
	global_load_dwordx4 v[28:31], v121, s[4:5]
	s_add_u32 s4, s4, 0x2000
	s_addc_u32 s5, s5, 0
	global_load_dwordx4 v[32:35], v121, s[4:5]
	s_add_u32 s4, s4, 0x2000
	s_addc_u32 s5, s5, 0
	s_waitcnt vmcnt(0)
	v_cmp_le_u32_e32 vcc, 1, v120
	s_nop 1
	v_cndmask_b32_e32 v0, 0, v0, vcc
	v_cndmask_b32_e32 v1, 0, v1, vcc
	v_cndmask_b32_e32 v2, 0, v2, vcc
	v_cndmask_b32_e32 v3, 0, v3, vcc
	v_lshlrev_b32_e32 v92, 16, v0
	v_and_b32_e32 v93, 0xffff0000, v0
	v_lshlrev_b32_e32 v94, 16, v1
	v_and_b32_e32 v95, 0xffff0000, v1
	v_lshlrev_b32_e32 v96, 16, v2
	v_and_b32_e32 v97, 0xffff0000, v2
	v_lshlrev_b32_e32 v98, 16, v3
	v_and_b32_e32 v99, 0xffff0000, v3
	v_add_u32_e32 v123, 1, v120
	v_min_u32_e32 v123, 2, v123
	v_cvt_f32_u32_e32 v112, v123
	v_div_scale_f32 v113, s[72:73], v112, v112, v118
	v_rcp_f32_e32 v114, v113
	v_div_scale_f32 v115, vcc, v118, v112, v118
	v_fma_f32 v116, -v113, v114, 1.0
	v_fmac_f32_e32 v114, v116, v114
	v_mul_f32_e32 v116, v115, v114
	v_fma_f32 v117, -v113, v116, v115
	v_fmac_f32_e32 v116, v117, v114
	v_fma_f32 v113, -v113, v116, v115
	v_div_fmas_f32 v113, v113, v114, v116
	v_div_fixup_f32 v119, v113, v112, v118
	v_lshlrev_b32_e32 v100, 16, v4
	v_and_b32_e32 v101, 0xffff0000, v4
	v_lshlrev_b32_e32 v102, 16, v5
	v_and_b32_e32 v103, 0xffff0000, v5
	v_lshlrev_b32_e32 v104, 16, v6
	v_and_b32_e32 v105, 0xffff0000, v6
	v_lshlrev_b32_e32 v106, 16, v7
	v_and_b32_e32 v107, 0xffff0000, v7
	v_add_f32_e32 v92, v92, v100
	v_add_f32_e32 v93, v93, v101
	v_add_f32_e32 v94, v94, v102
	v_add_f32_e32 v95, v95, v103
	v_add_f32_e32 v96, v96, v104
	v_add_f32_e32 v97, v97, v105
	v_add_f32_e32 v98, v98, v106
	v_add_f32_e32 v99, v99, v107
	v_fma_f32 v100, v92, v119, -v100
	v_fma_f32 v101, v93, v119, -v101
	v_fma_f32 v102, v94, v119, -v102
	v_fma_f32 v103, v95, v119, -v103
	v_fma_f32 v104, v96, v119, -v104
	v_fma_f32 v105, v97, v119, -v105
	v_fma_f32 v106, v98, v119, -v106
	v_fma_f32 v107, v99, v119, -v107
	v_cvt_pk_bf16_f32 v108, v100, v101
	v_cvt_pk_bf16_f32 v109, v102, v103
	v_cvt_pk_bf16_f32 v110, v104, v105
	v_cvt_pk_bf16_f32 v111, v106, v107
	global_store_dwordx4 v122, v[108:111], s[70:71]
	s_add_u32 s70, s70, 0x800
	s_addc_u32 s71, s71, 0
	v_lshlrev_b32_e32 v100, 16, v0
	v_and_b32_e32 v101, 0xffff0000, v0
	v_lshlrev_b32_e32 v102, 16, v1
	v_and_b32_e32 v103, 0xffff0000, v1
	v_lshlrev_b32_e32 v104, 16, v2
	v_and_b32_e32 v105, 0xffff0000, v2
	v_lshlrev_b32_e32 v106, 16, v3
	v_and_b32_e32 v107, 0xffff0000, v3
	v_sub_f32_e32 v92, v92, v100
	v_sub_f32_e32 v93, v93, v101
	v_sub_f32_e32 v94, v94, v102
	v_sub_f32_e32 v95, v95, v103
	v_sub_f32_e32 v96, v96, v104
	v_sub_f32_e32 v97, v97, v105
	v_sub_f32_e32 v98, v98, v106
	v_sub_f32_e32 v99, v99, v107
	v_mov_b32_e32 v119, 0x3f000000
	v_lshlrev_b32_e32 v100, 16, v8
	v_and_b32_e32 v101, 0xffff0000, v8
	v_lshlrev_b32_e32 v102, 16, v9
	v_and_b32_e32 v103, 0xffff0000, v9
	v_lshlrev_b32_e32 v104, 16, v10
	v_and_b32_e32 v105, 0xffff0000, v10
	v_lshlrev_b32_e32 v106, 16, v11
	v_and_b32_e32 v107, 0xffff0000, v11
	v_add_f32_e32 v92, v92, v100
	v_add_f32_e32 v93, v93, v101
	v_add_f32_e32 v94, v94, v102
	v_add_f32_e32 v95, v95, v103
	v_add_f32_e32 v96, v96, v104
	v_add_f32_e32 v97, v97, v105
	v_add_f32_e32 v98, v98, v106
	v_add_f32_e32 v99, v99, v107
	v_fma_f32 v100, v92, v119, -v100
	v_fma_f32 v101, v93, v119, -v101
	v_fma_f32 v102, v94, v119, -v102
	v_fma_f32 v103, v95, v119, -v103
	v_fma_f32 v104, v96, v119, -v104
	v_fma_f32 v105, v97, v119, -v105
	v_fma_f32 v106, v98, v119, -v106
	v_fma_f32 v107, v99, v119, -v107
	v_cvt_pk_bf16_f32 v108, v100, v101
	v_cvt_pk_bf16_f32 v109, v102, v103
	v_cvt_pk_bf16_f32 v110, v104, v105
	v_cvt_pk_bf16_f32 v111, v106, v107
	global_store_dwordx4 v122, v[108:111], s[70:71]
	s_add_u32 s70, s70, 0x800
	s_addc_u32 s71, s71, 0
	v_lshlrev_b32_e32 v100, 16, v4
	v_and_b32_e32 v101, 0xffff0000, v4
	v_lshlrev_b32_e32 v102, 16, v5
	v_and_b32_e32 v103, 0xffff0000, v5
	v_lshlrev_b32_e32 v104, 16, v6
	v_and_b32_e32 v105, 0xffff0000, v6
	v_lshlrev_b32_e32 v106, 16, v7
	v_and_b32_e32 v107, 0xffff0000, v7
	v_sub_f32_e32 v92, v92, v100
	v_sub_f32_e32 v93, v93, v101
	v_sub_f32_e32 v94, v94, v102
	v_sub_f32_e32 v95, v95, v103
	v_sub_f32_e32 v96, v96, v104
	v_sub_f32_e32 v97, v97, v105
	v_sub_f32_e32 v98, v98, v106
	v_sub_f32_e32 v99, v99, v107
	v_lshlrev_b32_e32 v100, 16, v12
	v_and_b32_e32 v101, 0xffff0000, v12
	v_lshlrev_b32_e32 v102, 16, v13
	v_and_b32_e32 v103, 0xffff0000, v13
	v_lshlrev_b32_e32 v104, 16, v14
	v_and_b32_e32 v105, 0xffff0000, v14
	v_lshlrev_b32_e32 v106, 16, v15
	v_and_b32_e32 v107, 0xffff0000, v15
	v_add_f32_e32 v92, v92, v100
	v_add_f32_e32 v93, v93, v101
	v_add_f32_e32 v94, v94, v102
	v_add_f32_e32 v95, v95, v103
	v_add_f32_e32 v96, v96, v104
	v_add_f32_e32 v97, v97, v105
	v_add_f32_e32 v98, v98, v106
	v_add_f32_e32 v99, v99, v107
	v_fma_f32 v100, v92, v119, -v100
	v_fma_f32 v101, v93, v119, -v101
	v_fma_f32 v102, v94, v119, -v102
	v_fma_f32 v103, v95, v119, -v103
	v_fma_f32 v104, v96, v119, -v104
	v_fma_f32 v105, v97, v119, -v105
	v_fma_f32 v106, v98, v119, -v106
	v_fma_f32 v107, v99, v119, -v107
	v_cvt_pk_bf16_f32 v108, v100, v101
	v_cvt_pk_bf16_f32 v109, v102, v103
	v_cvt_pk_bf16_f32 v110, v104, v105
	v_cvt_pk_bf16_f32 v111, v106, v107
	global_store_dwordx4 v122, v[108:111], s[70:71]
	s_add_u32 s70, s70, 0x800
	s_addc_u32 s71, s71, 0
	v_lshlrev_b32_e32 v100, 16, v8
	v_and_b32_e32 v101, 0xffff0000, v8
	v_lshlrev_b32_e32 v102, 16, v9
	v_and_b32_e32 v103, 0xffff0000, v9
	v_lshlrev_b32_e32 v104, 16, v10
	v_and_b32_e32 v105, 0xffff0000, v10
	v_lshlrev_b32_e32 v106, 16, v11
	v_and_b32_e32 v107, 0xffff0000, v11
	v_sub_f32_e32 v92, v92, v100
	v_sub_f32_e32 v93, v93, v101
	v_sub_f32_e32 v94, v94, v102
	v_sub_f32_e32 v95, v95, v103
	v_sub_f32_e32 v96, v96, v104
	v_sub_f32_e32 v97, v97, v105
	v_sub_f32_e32 v98, v98, v106
	v_sub_f32_e32 v99, v99, v107
	v_lshlrev_b32_e32 v100, 16, v16
	v_and_b32_e32 v101, 0xffff0000, v16
	v_lshlrev_b32_e32 v102, 16, v17
	v_and_b32_e32 v103, 0xffff0000, v17
	v_lshlrev_b32_e32 v104, 16, v18
	v_and_b32_e32 v105, 0xffff0000, v18
	v_lshlrev_b32_e32 v106, 16, v19
	v_and_b32_e32 v107, 0xffff0000, v19
	v_add_f32_e32 v92, v92, v100
	v_add_f32_e32 v93, v93, v101
	v_add_f32_e32 v94, v94, v102
	v_add_f32_e32 v95, v95, v103
	v_add_f32_e32 v96, v96, v104
	v_add_f32_e32 v97, v97, v105
	v_add_f32_e32 v98, v98, v106
	v_add_f32_e32 v99, v99, v107
	v_fma_f32 v100, v92, v119, -v100
	v_fma_f32 v101, v93, v119, -v101
	v_fma_f32 v102, v94, v119, -v102
	v_fma_f32 v103, v95, v119, -v103
	v_fma_f32 v104, v96, v119, -v104
	v_fma_f32 v105, v97, v119, -v105
	v_fma_f32 v106, v98, v119, -v106
	v_fma_f32 v107, v99, v119, -v107
	v_cvt_pk_bf16_f32 v108, v100, v101
	v_cvt_pk_bf16_f32 v109, v102, v103
	v_cvt_pk_bf16_f32 v110, v104, v105
	v_cvt_pk_bf16_f32 v111, v106, v107
	global_store_dwordx4 v122, v[108:111], s[70:71]
	s_add_u32 s70, s70, 0x800
	s_addc_u32 s71, s71, 0
	v_lshlrev_b32_e32 v100, 16, v12
	v_and_b32_e32 v101, 0xffff0000, v12
	v_lshlrev_b32_e32 v102, 16, v13
	v_and_b32_e32 v103, 0xffff0000, v13
	v_lshlrev_b32_e32 v104, 16, v14
	v_and_b32_e32 v105, 0xffff0000, v14
	v_lshlrev_b32_e32 v106, 16, v15
	v_and_b32_e32 v107, 0xffff0000, v15
	v_sub_f32_e32 v92, v92, v100
	v_sub_f32_e32 v93, v93, v101
	v_sub_f32_e32 v94, v94, v102
	v_sub_f32_e32 v95, v95, v103
	v_sub_f32_e32 v96, v96, v104
	v_sub_f32_e32 v97, v97, v105
	v_sub_f32_e32 v98, v98, v106
	v_sub_f32_e32 v99, v99, v107
	v_lshlrev_b32_e32 v100, 16, v20
	v_and_b32_e32 v101, 0xffff0000, v20
	v_lshlrev_b32_e32 v102, 16, v21
	v_and_b32_e32 v103, 0xffff0000, v21
	v_lshlrev_b32_e32 v104, 16, v22
	v_and_b32_e32 v105, 0xffff0000, v22
	v_lshlrev_b32_e32 v106, 16, v23
	v_and_b32_e32 v107, 0xffff0000, v23
	v_add_f32_e32 v92, v92, v100
	v_add_f32_e32 v93, v93, v101
	v_add_f32_e32 v94, v94, v102
	v_add_f32_e32 v95, v95, v103
	v_add_f32_e32 v96, v96, v104
	v_add_f32_e32 v97, v97, v105
	v_add_f32_e32 v98, v98, v106
	v_add_f32_e32 v99, v99, v107
	v_fma_f32 v100, v92, v119, -v100
	v_fma_f32 v101, v93, v119, -v101
	v_fma_f32 v102, v94, v119, -v102
	v_fma_f32 v103, v95, v119, -v103
	v_fma_f32 v104, v96, v119, -v104
	v_fma_f32 v105, v97, v119, -v105
	v_fma_f32 v106, v98, v119, -v106
	v_fma_f32 v107, v99, v119, -v107
	v_cvt_pk_bf16_f32 v108, v100, v101
	v_cvt_pk_bf16_f32 v109, v102, v103
	v_cvt_pk_bf16_f32 v110, v104, v105
	v_cvt_pk_bf16_f32 v111, v106, v107
	global_store_dwordx4 v122, v[108:111], s[70:71]
	s_add_u32 s70, s70, 0x800
	s_addc_u32 s71, s71, 0
	v_lshlrev_b32_e32 v100, 16, v16
	v_and_b32_e32 v101, 0xffff0000, v16
	v_lshlrev_b32_e32 v102, 16, v17
	v_and_b32_e32 v103, 0xffff0000, v17
	v_lshlrev_b32_e32 v104, 16, v18
	v_and_b32_e32 v105, 0xffff0000, v18
	v_lshlrev_b32_e32 v106, 16, v19
	v_and_b32_e32 v107, 0xffff0000, v19
	v_sub_f32_e32 v92, v92, v100
	v_sub_f32_e32 v93, v93, v101
	v_sub_f32_e32 v94, v94, v102
	v_sub_f32_e32 v95, v95, v103
	v_sub_f32_e32 v96, v96, v104
	v_sub_f32_e32 v97, v97, v105
	v_sub_f32_e32 v98, v98, v106
	v_sub_f32_e32 v99, v99, v107
	v_lshlrev_b32_e32 v100, 16, v24
	v_and_b32_e32 v101, 0xffff0000, v24
	v_lshlrev_b32_e32 v102, 16, v25
	v_and_b32_e32 v103, 0xffff0000, v25
	v_lshlrev_b32_e32 v104, 16, v26
	v_and_b32_e32 v105, 0xffff0000, v26
	v_lshlrev_b32_e32 v106, 16, v27
	v_and_b32_e32 v107, 0xffff0000, v27
	v_add_f32_e32 v92, v92, v100
	v_add_f32_e32 v93, v93, v101
	v_add_f32_e32 v94, v94, v102
	v_add_f32_e32 v95, v95, v103
	v_add_f32_e32 v96, v96, v104
	v_add_f32_e32 v97, v97, v105
	v_add_f32_e32 v98, v98, v106
	v_add_f32_e32 v99, v99, v107
	v_fma_f32 v100, v92, v119, -v100
	v_fma_f32 v101, v93, v119, -v101
	v_fma_f32 v102, v94, v119, -v102
	v_fma_f32 v103, v95, v119, -v103
	v_fma_f32 v104, v96, v119, -v104
	v_fma_f32 v105, v97, v119, -v105
	v_fma_f32 v106, v98, v119, -v106
	v_fma_f32 v107, v99, v119, -v107
	v_cvt_pk_bf16_f32 v108, v100, v101
	v_cvt_pk_bf16_f32 v109, v102, v103
	v_cvt_pk_bf16_f32 v110, v104, v105
	v_cvt_pk_bf16_f32 v111, v106, v107
	global_store_dwordx4 v122, v[108:111], s[70:71]
	s_add_u32 s70, s70, 0x800
	s_addc_u32 s71, s71, 0
	v_lshlrev_b32_e32 v100, 16, v20
	v_and_b32_e32 v101, 0xffff0000, v20
	v_lshlrev_b32_e32 v102, 16, v21
	v_and_b32_e32 v103, 0xffff0000, v21
	v_lshlrev_b32_e32 v104, 16, v22
	v_and_b32_e32 v105, 0xffff0000, v22
	v_lshlrev_b32_e32 v106, 16, v23
	v_and_b32_e32 v107, 0xffff0000, v23
	v_sub_f32_e32 v92, v92, v100
	v_sub_f32_e32 v93, v93, v101
	v_sub_f32_e32 v94, v94, v102
	v_sub_f32_e32 v95, v95, v103
	v_sub_f32_e32 v96, v96, v104
	v_sub_f32_e32 v97, v97, v105
	v_sub_f32_e32 v98, v98, v106
	v_sub_f32_e32 v99, v99, v107
	v_lshlrev_b32_e32 v100, 16, v28
	v_and_b32_e32 v101, 0xffff0000, v28
	v_lshlrev_b32_e32 v102, 16, v29
	v_and_b32_e32 v103, 0xffff0000, v29
	v_lshlrev_b32_e32 v104, 16, v30
	v_and_b32_e32 v105, 0xffff0000, v30
	v_lshlrev_b32_e32 v106, 16, v31
	v_and_b32_e32 v107, 0xffff0000, v31
	v_add_f32_e32 v92, v92, v100
	v_add_f32_e32 v93, v93, v101
	v_add_f32_e32 v94, v94, v102
	v_add_f32_e32 v95, v95, v103
	v_add_f32_e32 v96, v96, v104
	v_add_f32_e32 v97, v97, v105
	v_add_f32_e32 v98, v98, v106
	v_add_f32_e32 v99, v99, v107
	v_fma_f32 v100, v92, v119, -v100
	v_fma_f32 v101, v93, v119, -v101
	v_fma_f32 v102, v94, v119, -v102
	v_fma_f32 v103, v95, v119, -v103
	v_fma_f32 v104, v96, v119, -v104
	v_fma_f32 v105, v97, v119, -v105
	v_fma_f32 v106, v98, v119, -v106
	v_fma_f32 v107, v99, v119, -v107
	v_cvt_pk_bf16_f32 v108, v100, v101
	v_cvt_pk_bf16_f32 v109, v102, v103
	v_cvt_pk_bf16_f32 v110, v104, v105
	v_cvt_pk_bf16_f32 v111, v106, v107
	global_store_dwordx4 v122, v[108:111], s[70:71]
	s_add_u32 s70, s70, 0x800
	s_addc_u32 s71, s71, 0
	v_lshlrev_b32_e32 v100, 16, v24
	v_and_b32_e32 v101, 0xffff0000, v24
	v_lshlrev_b32_e32 v102, 16, v25
	v_and_b32_e32 v103, 0xffff0000, v25
	v_lshlrev_b32_e32 v104, 16, v26
	v_and_b32_e32 v105, 0xffff0000, v26
	v_lshlrev_b32_e32 v106, 16, v27
	v_and_b32_e32 v107, 0xffff0000, v27
	v_sub_f32_e32 v92, v92, v100
	v_sub_f32_e32 v93, v93, v101
	v_sub_f32_e32 v94, v94, v102
	v_sub_f32_e32 v95, v95, v103
	v_sub_f32_e32 v96, v96, v104
	v_sub_f32_e32 v97, v97, v105
	v_sub_f32_e32 v98, v98, v106
	v_sub_f32_e32 v99, v99, v107
	v_lshlrev_b32_e32 v100, 16, v32
	v_and_b32_e32 v101, 0xffff0000, v32
	v_lshlrev_b32_e32 v102, 16, v33
	v_and_b32_e32 v103, 0xffff0000, v33
	v_lshlrev_b32_e32 v104, 16, v34
	v_and_b32_e32 v105, 0xffff0000, v34
	v_lshlrev_b32_e32 v106, 16, v35
	v_and_b32_e32 v107, 0xffff0000, v35
	v_add_f32_e32 v92, v92, v100
	v_add_f32_e32 v93, v93, v101
	v_add_f32_e32 v94, v94, v102
	v_add_f32_e32 v95, v95, v103
	v_add_f32_e32 v96, v96, v104
	v_add_f32_e32 v97, v97, v105
	v_add_f32_e32 v98, v98, v106
	v_add_f32_e32 v99, v99, v107
	v_fma_f32 v100, v92, v119, -v100
	v_fma_f32 v101, v93, v119, -v101
	v_fma_f32 v102, v94, v119, -v102
	v_fma_f32 v103, v95, v119, -v103
	v_fma_f32 v104, v96, v119, -v104
	v_fma_f32 v105, v97, v119, -v105
	v_fma_f32 v106, v98, v119, -v106
	v_fma_f32 v107, v99, v119, -v107
	v_cvt_pk_bf16_f32 v108, v100, v101
	v_cvt_pk_bf16_f32 v109, v102, v103
	v_cvt_pk_bf16_f32 v110, v104, v105
	v_cvt_pk_bf16_f32 v111, v106, v107
	global_store_dwordx4 v122, v[108:111], s[70:71]
	s_add_u32 s70, s70, 0x800
	s_addc_u32 s71, s71, 0
	s_add_u32 s8, s8, 1
	s_cmp_lt_u32 s8, 2
	s_cbranch_scc0 .Lpl_done
	s_add_u32 s4, s68, 0xfe000
	s_addc_u32 s5, s69, 0
	s_add_u32 s70, s66, 0x40000
	s_addc_u32 s71, s67, 0
	v_add_u32_e32 v120, 0x80, v120
	s_branch .Lpl_w2_pass
.Lpl_w4:
	s_sub_u32 s4, s68, 0x6000
	s_subb_u32 s5, s69, 0
	s_mov_b32 s70, s66
	s_mov_b32 s71, s67
	s_mov_b32 s8, 0
.Lpl_w4_pass:
	global_load_dwordx4 v[0:3], v121, s[4:5]
	s_add_u32 s4, s4, 0x2000
	s_addc_u32 s5, s5, 0
	global_load_dwordx4 v[4:7], v121, s[4:5]
	s_add_u32 s4, s4, 0x2000
	s_addc_u32 s5, s5, 0
	global_load_dwordx4 v[8:11], v121, s[4:5]
	s_add_u32 s4, s4, 0x2000
	s_addc_u32 s5, s5, 0
	global_load_dwordx4 v[12:15], v121, s[4:5]
	s_add_u32 s4, s4, 0x2000
	s_addc_u32 s5, s5, 0
	global_load_dwordx4 v[16:19], v121, s[4:5]
	s_add_u32 s4, s4, 0x2000
	s_addc_u32 s5, s5, 0
	global_load_dwordx4 v[20:23], v121, s[4:5]
	s_add_u32 s4, s4, 0x2000
	s_addc_u32 s5, s5, 0
	global_load_dwordx4 v[24:27], v121, s[4:5]
	s_add_u32 s4, s4, 0x2000
	s_addc_u32 s5, s5, 0
	global_load_dwordx4 v[28:31], v121, s[4:5]
	s_add_u32 s4, s4, 0x2000
	s_addc_u32 s5, s5, 0
	global_load_dwordx4 v[32:35], v121, s[4:5]
	s_add_u32 s4, s4, 0x2000
	s_addc_u32 s5, s5, 0
	global_load_dwordx4 v[36:39], v121, s[4:5]
	s_add_u32 s4, s4, 0x2000
	s_addc_u32 s5, s5, 0
	global_load_dwordx4 v[40:43], v121, s[4:5]
	s_add_u32 s4, s4, 0x2000
	s_addc_u32 s5, s5, 0
	s_waitcnt vmcnt(0)
	v_cmp_le_u32_e32 vcc, 3, v120
	s_nop 1
	v_cndmask_b32_e32 v0, 0, v0, vcc
	v_cndmask_b32_e32 v1, 0, v1, vcc
	v_cndmask_b32_e32 v2, 0, v2, vcc
	v_cndmask_b32_e32 v3, 0, v3, vcc
	v_cmp_le_u32_e32 vcc, 2, v120
	s_nop 1
	v_cndmask_b32_e32 v4, 0, v4, vcc
	v_cndmask_b32_e32 v5, 0, v5, vcc
	v_cndmask_b32_e32 v6, 0, v6, vcc
	v_cndmask_b32_e32 v7, 0, v7, vcc
	v_cmp_le_u32_e32 vcc, 1, v120
	s_nop 1
	v_cndmask_b32_e32 v8, 0, v8, vcc
	v_cndmask_b32_e32 v9, 0, v9, vcc
	v_cndmask_b32_e32 v10, 0, v10, vcc
	v_cndmask_b32_e32 v11, 0, v11, vcc
	v_lshlrev_b32_e32 v92, 16, v0
	v_and_b32_e32 v93, 0xffff0000, v0
	v_lshlrev_b32_e32 v94, 16, v1
	v_and_b32_e32 v95, 0xffff0000, v1
	v_lshlrev_b32_e32 v96, 16, v2
	v_and_b32_e32 v97, 0xffff0000, v2
	v_lshlrev_b32_e32 v98, 16, v3
	v_and_b32_e32 v99, 0xffff0000, v3
	v_lshlrev_b32_e32 v100, 16, v4
	v_and_b32_e32 v101, 0xffff0000, v4
	v_lshlrev_b32_e32 v102, 16, v5
	v_and_b32_e32 v103, 0xffff0000, v5
	v_lshlrev_b32_e32 v104, 16, v6
	v_and_b32_e32 v105, 0xffff0000, v6
	v_lshlrev_b32_e32 v106, 16, v7
	v_and_b32_e32 v107, 0xffff0000, v7
	v_add_f32_e32 v92, v92, v100
	v_add_f32_e32 v93, v93, v101
	v_add_f32_e32 v94, v94, v102
	v_add_f32_e32 v95, v95, v103
	v_add_f32_e32 v96, v96, v104
	v_add_f32_e32 v97, v97, v105
	v_add_f32_e32 v98, v98, v106
	v_add_f32_e32 v99, v99, v107
	v_lshlrev_b32_e32 v100, 16, v8
	v_and_b32_e32 v101, 0xffff0000, v8
	v_lshlrev_b32_e32 v102, 16, v9
	v_and_b32_e32 v103, 0xffff0000, v9
	v_lshlrev_b32_e32 v104, 16, v10
	v_and_b32_e32 v105, 0xffff0000, v10
	v_lshlrev_b32_e32 v106, 16, v11
	v_and_b32_e32 v107, 0xffff0000, v11
	v_add_f32_e32 v92, v92, v100
	v_add_f32_e32 v93, v93, v101
	v_add_f32_e32 v94, v94, v102
	v_add_f32_e32 v95, v95, v103
	v_add_f32_e32 v96, v96, v104
	v_add_f32_e32 v97, v97, v105
	v_add_f32_e32 v98, v98, v106
	v_add_f32_e32 v99, v99, v107
	v_add_u32_e32 v123, 1, v120
	v_min_u32_e32 v123, 4, v123
	v_cvt_f32_u32_e32 v112, v123
	v_div_scale_f32 v113, s[72:73], v112, v112, v118
	v_rcp_f32_e32 v114, v113
	v_div_scale_f32 v115, vcc, v118, v112, v118
	v_fma_f32 v116, -v113, v114, 1.0
	v_fmac_f32_e32 v114, v116, v114
	v_mul_f32_e32 v116, v115, v114
	v_fma_f32 v117, -v113, v116, v115
	v_fmac_f32_e32 v116, v117, v114
	v_fma_f32 v113, -v113, v116, v115
	v_div_fmas_f32 v113, v113, v114, v116
	v_div_fixup_f32 v119, v113, v112, v118
	v_lshlrev_b32_e32 v100, 16, v12
	v_and_b32_e32 v101, 0xffff0000, v12
	v_lshlrev_b32_e32 v102, 16, v13
	v_and_b32_e32 v103, 0xffff0000, v13
	v_lshlrev_b32_e32 v104, 16, v14
	v_and_b32_e32 v105, 0xffff0000, v14
	v_lshlrev_b32_e32 v106, 16, v15
	v_and_b32_e32 v107, 0xffff0000, v15
	v_add_f32_e32 v92, v92, v100
	v_add_f32_e32 v93, v93, v101
	v_add_f32_e32 v94, v94, v102
	v_add_f32_e32 v95, v95, v103
	v_add_f32_e32 v96, v96, v104
	v_add_f32_e32 v97, v97, v105
	v_add_f32_e32 v98, v98, v106
	v_add_f32_e32 v99, v99, v107
	v_fma_f32 v100, v92, v119, -v100
	v_fma_f32 v101, v93, v119, -v101
	v_fma_f32 v102, v94, v119, -v102
	v_fma_f32 v103, v95, v119, -v103
	v_fma_f32 v104, v96, v119, -v104
	v_fma_f32 v105, v97, v119, -v105
	v_fma_f32 v106, v98, v119, -v106
	v_fma_f32 v107, v99, v119, -v107
	v_cvt_pk_bf16_f32 v108, v100, v101
	v_cvt_pk_bf16_f32 v109, v102, v103
	v_cvt_pk_bf16_f32 v110, v104, v105
	v_cvt_pk_bf16_f32 v111, v106, v107
	global_store_dwordx4 v122, v[108:111], s[70:71]
	s_add_u32 s70, s70, 0x800
	s_addc_u32 s71, s71, 0
	v_lshlrev_b32_e32 v100, 16, v0
	v_and_b32_e32 v101, 0xffff0000, v0
	v_lshlrev_b32_e32 v102, 16, v1
	v_and_b32_e32 v103, 0xffff0000, v1
	v_lshlrev_b32_e32 v104, 16, v2
	v_and_b32_e32 v105, 0xffff0000, v2
	v_lshlrev_b32_e32 v106, 16, v3
	v_and_b32_e32 v107, 0xffff0000, v3
	v_sub_f32_e32 v92, v92, v100
	v_sub_f32_e32 v93, v93, v101
	v_sub_f32_e32 v94, v94, v102
	v_sub_f32_e32 v95, v95, v103
	v_sub_f32_e32 v96, v96, v104
	v_sub_f32_e32 v97, v97, v105
	v_sub_f32_e32 v98, v98, v106
	v_sub_f32_e32 v99, v99, v107
	v_add_u32_e32 v123, 2, v120
	v_min_u32_e32 v123, 4, v123
	v_cvt_f32_u32_e32 v112, v123
	v_div_scale_f32 v113, s[72:73], v112, v112, v118
	v_rcp_f32_e32 v114, v113
	v_div_scale_f32 v115, vcc, v118, v112, v118
	v_fma_f32 v116, -v113, v114, 1.0
	v_fmac_f32_e32 v114, v116, v114
	v_mul_f32_e32 v116, v115, v114
	v_fma_f32 v117, -v113, v116, v115
	v_fmac_f32_e32 v116, v117, v114
	v_fma_f32 v113, -v113, v116, v115
	v_div_fmas_f32 v113, v113, v114, v116
	v_div_fixup_f32 v119, v113, v112, v118
	v_lshlrev_b32_e32 v100, 16, v16
	v_and_b32_e32 v101, 0xffff0000, v16
	v_lshlrev_b32_e32 v102, 16, v17
	v_and_b32_e32 v103, 0xffff0000, v17
	v_lshlrev_b32_e32 v104, 16, v18
	v_and_b32_e32 v105, 0xffff0000, v18
	v_lshlrev_b32_e32 v106, 16, v19
	v_and_b32_e32 v107, 0xffff0000, v19
	v_add_f32_e32 v92, v92, v100
	v_add_f32_e32 v93, v93, v101
	v_add_f32_e32 v94, v94, v102
	v_add_f32_e32 v95, v95, v103
	v_add_f32_e32 v96, v96, v104
	v_add_f32_e32 v97, v97, v105
	v_add_f32_e32 v98, v98, v106
	v_add_f32_e32 v99, v99, v107
	v_fma_f32 v100, v92, v119, -v100
	v_fma_f32 v101, v93, v119, -v101
	v_fma_f32 v102, v94, v119, -v102
	v_fma_f32 v103, v95, v119, -v103
	v_fma_f32 v104, v96, v119, -v104
	v_fma_f32 v105, v97, v119, -v105
	v_fma_f32 v106, v98, v119, -v106
	v_fma_f32 v107, v99, v119, -v107
	v_cvt_pk_bf16_f32 v108, v100, v101
	v_cvt_pk_bf16_f32 v109, v102, v103
	v_cvt_pk_bf16_f32 v110, v104, v105
	v_cvt_pk_bf16_f32 v111, v106, v107
	global_store_dwordx4 v122, v[108:111], s[70:71]
	s_add_u32 s70, s70, 0x800
	s_addc_u32 s71, s71, 0
	v_lshlrev_b32_e32 v100, 16, v4
	v_and_b32_e32 v101, 0xffff0000, v4
	v_lshlrev_b32_e32 v102, 16, v5
	v_and_b32_e32 v103, 0xffff0000, v5
	v_lshlrev_b32_e32 v104, 16, v6
	v_and_b32_e32 v105, 0xffff0000, v6
	v_lshlrev_b32_e32 v106, 16, v7
	v_and_b32_e32 v107, 0xffff0000, v7
	v_sub_f32_e32 v92, v92, v100
	v_sub_f32_e32 v93, v93, v101
	v_sub_f32_e32 v94, v94, v102
	v_sub_f32_e32 v95, v95, v103
	v_sub_f32_e32 v96, v96, v104
	v_sub_f32_e32 v97, v97, v105
	v_sub_f32_e32 v98, v98, v106
	v_sub_f32_e32 v99, v99, v107
	v_add_u32_e32 v123, 3, v120
	v_min_u32_e32 v123, 4, v123
	v_cvt_f32_u32_e32 v112, v123
	v_div_scale_f32 v113, s[72:73], v112, v112, v118
	v_rcp_f32_e32 v114, v113
	v_div_scale_f32 v115, vcc, v118, v112, v118
	v_fma_f32 v116, -v113, v114, 1.0
	v_fmac_f32_e32 v114, v116, v114
	v_mul_f32_e32 v116, v115, v114
	v_fma_f32 v117, -v113, v116, v115
	v_fmac_f32_e32 v116, v117, v114
	v_fma_f32 v113, -v113, v116, v115
	v_div_fmas_f32 v113, v113, v114, v116
	v_div_fixup_f32 v119, v113, v112, v118
	v_lshlrev_b32_e32 v100, 16, v20
	v_and_b32_e32 v101, 0xffff0000, v20
	v_lshlrev_b32_e32 v102, 16, v21
	v_and_b32_e32 v103, 0xffff0000, v21
	v_lshlrev_b32_e32 v104, 16, v22
	v_and_b32_e32 v105, 0xffff0000, v22
	v_lshlrev_b32_e32 v106, 16, v23
	v_and_b32_e32 v107, 0xffff0000, v23
	v_add_f32_e32 v92, v92, v100
	v_add_f32_e32 v93, v93, v101
	v_add_f32_e32 v94, v94, v102
	v_add_f32_e32 v95, v95, v103
	v_add_f32_e32 v96, v96, v104
	v_add_f32_e32 v97, v97, v105
	v_add_f32_e32 v98, v98, v106
	v_add_f32_e32 v99, v99, v107
	v_fma_f32 v100, v92, v119, -v100
	v_fma_f32 v101, v93, v119, -v101
	v_fma_f32 v102, v94, v119, -v102
	v_fma_f32 v103, v95, v119, -v103
	v_fma_f32 v104, v96, v119, -v104
	v_fma_f32 v105, v97, v119, -v105
	v_fma_f32 v106, v98, v119, -v106
	v_fma_f32 v107, v99, v119, -v107
	v_cvt_pk_bf16_f32 v108, v100, v101
	v_cvt_pk_bf16_f32 v109, v102, v103
	v_cvt_pk_bf16_f32 v110, v104, v105
	v_cvt_pk_bf16_f32 v111, v106, v107
	global_store_dwordx4 v122, v[108:111], s[70:71]
	s_add_u32 s70, s70, 0x800
	s_addc_u32 s71, s71, 0
	v_lshlrev_b32_e32 v100, 16, v8
	v_and_b32_e32 v101, 0xffff0000, v8
	v_lshlrev_b32_e32 v102, 16, v9
	v_and_b32_e32 v103, 0xffff0000, v9
	v_lshlrev_b32_e32 v104, 16, v10
	v_and_b32_e32 v105, 0xffff0000, v10
	v_lshlrev_b32_e32 v106, 16, v11
	v_and_b32_e32 v107, 0xffff0000, v11
	v_sub_f32_e32 v92, v92, v100
	v_sub_f32_e32 v93, v93, v101
	v_sub_f32_e32 v94, v94, v102
	v_sub_f32_e32 v95, v95, v103
	v_sub_f32_e32 v96, v96, v104
	v_sub_f32_e32 v97, v97, v105
	v_sub_f32_e32 v98, v98, v106
	v_sub_f32_e32 v99, v99, v107
	v_mov_b32_e32 v119, 0x3e800000
	v_lshlrev_b32_e32 v100, 16, v24
	v_and_b32_e32 v101, 0xffff0000, v24
	v_lshlrev_b32_e32 v102, 16, v25
	v_and_b32_e32 v103, 0xffff0000, v25
	v_lshlrev_b32_e32 v104, 16, v26
	v_and_b32_e32 v105, 0xffff0000, v26
	v_lshlrev_b32_e32 v106, 16, v27
	v_and_b32_e32 v107, 0xffff0000, v27
	v_add_f32_e32 v92, v92, v100
	v_add_f32_e32 v93, v93, v101
	v_add_f32_e32 v94, v94, v102
	v_add_f32_e32 v95, v95, v103
	v_add_f32_e32 v96, v96, v104
	v_add_f32_e32 v97, v97, v105
	v_add_f32_e32 v98, v98, v106
	v_add_f32_e32 v99, v99, v107
	v_fma_f32 v100, v92, v119, -v100
	v_fma_f32 v101, v93, v119, -v101
	v_fma_f32 v102, v94, v119, -v102
	v_fma_f32 v103, v95, v119, -v103
	v_fma_f32 v104, v96, v119, -v104
	v_fma_f32 v105, v97, v119, -v105
	v_fma_f32 v106, v98, v119, -v106
	v_fma_f32 v107, v99, v119, -v107
	v_cvt_pk_bf16_f32 v108, v100, v101
	v_cvt_pk_bf16_f32 v109, v102, v103
	v_cvt_pk_bf16_f32 v110, v104, v105
	v_cvt_pk_bf16_f32 v111, v106, v107
	global_store_dwordx4 v122, v[108:111], s[70:71]
	s_add_u32 s70, s70, 0x800
	s_addc_u32 s71, s71, 0
	v_lshlrev_b32_e32 v100, 16, v12
	v_and_b32_e32 v101, 0xffff0000, v12
	v_lshlrev_b32_e32 v102, 16, v13
	v_and_b32_e32 v103, 0xffff0000, v13
	v_lshlrev_b32_e32 v104, 16, v14
	v_and_b32_e32 v105, 0xffff0000, v14
	v_lshlrev_b32_e32 v106, 16, v15
	v_and_b32_e32 v107, 0xffff0000, v15
	v_sub_f32_e32 v92, v92, v100
	v_sub_f32_e32 v93, v93, v101
	v_sub_f32_e32 v94, v94, v102
	v_sub_f32_e32 v95, v95, v103
	v_sub_f32_e32 v96, v96, v104
	v_sub_f32_e32 v97, v97, v105
	v_sub_f32_e32 v98, v98, v106
	v_sub_f32_e32 v99, v99, v107
	v_lshlrev_b32_e32 v100, 16, v28
	v_and_b32_e32 v101, 0xffff0000, v28
	v_lshlrev_b32_e32 v102, 16, v29
	v_and_b32_e32 v103, 0xffff0000, v29
	v_lshlrev_b32_e32 v104, 16, v30
	v_and_b32_e32 v105, 0xffff0000, v30
	v_lshlrev_b32_e32 v106, 16, v31
	v_and_b32_e32 v107, 0xffff0000, v31
	v_add_f32_e32 v92, v92, v100
	v_add_f32_e32 v93, v93, v101
	v_add_f32_e32 v94, v94, v102
	v_add_f32_e32 v95, v95, v103
	v_add_f32_e32 v96, v96, v104
	v_add_f32_e32 v97, v97, v105
	v_add_f32_e32 v98, v98, v106
	v_add_f32_e32 v99, v99, v107
	v_fma_f32 v100, v92, v119, -v100
	v_fma_f32 v101, v93, v119, -v101
	v_fma_f32 v102, v94, v119, -v102
	v_fma_f32 v103, v95, v119, -v103
	v_fma_f32 v104, v96, v119, -v104
	v_fma_f32 v105, v97, v119, -v105
	v_fma_f32 v106, v98, v119, -v106
	v_fma_f32 v107, v99, v119, -v107
	v_cvt_pk_bf16_f32 v108, v100, v101
	v_cvt_pk_bf16_f32 v109, v102, v103
	v_cvt_pk_bf16_f32 v110, v104, v105
	v_cvt_pk_bf16_f32 v111, v106, v107
	global_store_dwordx4 v122, v[108:111], s[70:71]
	s_add_u32 s70, s70, 0x800
	s_addc_u32 s71, s71, 0
	v_lshlrev_b32_e32 v100, 16, v16
	v_and_b32_e32 v101, 0xffff0000, v16
	v_lshlrev_b32_e32 v102, 16, v17
	v_and_b32_e32 v103, 0xffff0000, v17
	v_lshlrev_b32_e32 v104, 16, v18
	v_and_b32_e32 v105, 0xffff0000, v18
	v_lshlrev_b32_e32 v106, 16, v19
	v_and_b32_e32 v107, 0xffff0000, v19
	v_sub_f32_e32 v92, v92, v100
	v_sub_f32_e32 v93, v93, v101
	v_sub_f32_e32 v94, v94, v102
	v_sub_f32_e32 v95, v95, v103
	v_sub_f32_e32 v96, v96, v104
	v_sub_f32_e32 v97, v97, v105
	v_sub_f32_e32 v98, v98, v106
	v_sub_f32_e32 v99, v99, v107
	v_lshlrev_b32_e32 v100, 16, v32
	v_and_b32_e32 v101, 0xffff0000, v32
	v_lshlrev_b32_e32 v102, 16, v33
	v_and_b32_e32 v103, 0xffff0000, v33
	v_lshlrev_b32_e32 v104, 16, v34
	v_and_b32_e32 v105, 0xffff0000, v34
	v_lshlrev_b32_e32 v106, 16, v35
	v_and_b32_e32 v107, 0xffff0000, v35
	v_add_f32_e32 v92, v92, v100
	v_add_f32_e32 v93, v93, v101
	v_add_f32_e32 v94, v94, v102
	v_add_f32_e32 v95, v95, v103
	v_add_f32_e32 v96, v96, v104
	v_add_f32_e32 v97, v97, v105
	v_add_f32_e32 v98, v98, v106
	v_add_f32_e32 v99, v99, v107
	v_fma_f32 v100, v92, v119, -v100
	v_fma_f32 v101, v93, v119, -v101
	v_fma_f32 v102, v94, v119, -v102
	v_fma_f32 v103, v95, v119, -v103
	v_fma_f32 v104, v96, v119, -v104
	v_fma_f32 v105, v97, v119, -v105
	v_fma_f32 v106, v98, v119, -v106
	v_fma_f32 v107, v99, v119, -v107
	v_cvt_pk_bf16_f32 v108, v100, v101
	v_cvt_pk_bf16_f32 v109, v102, v103
	v_cvt_pk_bf16_f32 v110, v104, v105
	v_cvt_pk_bf16_f32 v111, v106, v107
	global_store_dwordx4 v122, v[108:111], s[70:71]
	s_add_u32 s70, s70, 0x800
	s_addc_u32 s71, s71, 0
	v_lshlrev_b32_e32 v100, 16, v20
	v_and_b32_e32 v101, 0xffff0000, v20
	v_lshlrev_b32_e32 v102, 16, v21
	v_and_b32_e32 v103, 0xffff0000, v21
	v_lshlrev_b32_e32 v104, 16, v22
	v_and_b32_e32 v105, 0xffff0000, v22
	v_lshlrev_b32_e32 v106, 16, v23
	v_and_b32_e32 v107, 0xffff0000, v23
	v_sub_f32_e32 v92, v92, v100
	v_sub_f32_e32 v93, v93, v101
	v_sub_f32_e32 v94, v94, v102
	v_sub_f32_e32 v95, v95, v103
	v_sub_f32_e32 v96, v96, v104
	v_sub_f32_e32 v97, v97, v105
	v_sub_f32_e32 v98, v98, v106
	v_sub_f32_e32 v99, v99, v107
	v_lshlrev_b32_e32 v100, 16, v36
	v_and_b32_e32 v101, 0xffff0000, v36
	v_lshlrev_b32_e32 v102, 16, v37
	v_and_b32_e32 v103, 0xffff0000, v37
	v_lshlrev_b32_e32 v104, 16, v38
	v_and_b32_e32 v105, 0xffff0000, v38
	v_lshlrev_b32_e32 v106, 16, v39
	v_and_b32_e32 v107, 0xffff0000, v39
	v_add_f32_e32 v92, v92, v100
	v_add_f32_e32 v93, v93, v101
	v_add_f32_e32 v94, v94, v102
	v_add_f32_e32 v95, v95, v103
	v_add_f32_e32 v96, v96, v104
	v_add_f32_e32 v97, v97, v105
	v_add_f32_e32 v98, v98, v106
	v_add_f32_e32 v99, v99, v107
	v_fma_f32 v100, v92, v119, -v100
	v_fma_f32 v101, v93, v119, -v101
	v_fma_f32 v102, v94, v119, -v102
	v_fma_f32 v103, v95, v119, -v103
	v_fma_f32 v104, v96, v119, -v104
	v_fma_f32 v105, v97, v119, -v105
	v_fma_f32 v106, v98, v119, -v106
	v_fma_f32 v107, v99, v119, -v107
	v_cvt_pk_bf16_f32 v108, v100, v101
	v_cvt_pk_bf16_f32 v109, v102, v103
	v_cvt_pk_bf16_f32 v110, v104, v105
	v_cvt_pk_bf16_f32 v111, v106, v107
	global_store_dwordx4 v122, v[108:111], s[70:71]
	s_add_u32 s70, s70, 0x800
	s_addc_u32 s71, s71, 0
	v_lshlrev_b32_e32 v100, 16, v24
	v_and_b32_e32 v101, 0xffff0000, v24
	v_lshlrev_b32_e32 v102, 16, v25
	v_and_b32_e32 v103, 0xffff0000, v25
	v_lshlrev_b32_e32 v104, 16, v26
	v_and_b32_e32 v105, 0xffff0000, v26
	v_lshlrev_b32_e32 v106, 16, v27
	v_and_b32_e32 v107, 0xffff0000, v27
	v_sub_f32_e32 v92, v92, v100
	v_sub_f32_e32 v93, v93, v101
	v_sub_f32_e32 v94, v94, v102
	v_sub_f32_e32 v95, v95, v103
	v_sub_f32_e32 v96, v96, v104
	v_sub_f32_e32 v97, v97, v105
	v_sub_f32_e32 v98, v98, v106
	v_sub_f32_e32 v99, v99, v107
	v_lshlrev_b32_e32 v100, 16, v40
	v_and_b32_e32 v101, 0xffff0000, v40
	v_lshlrev_b32_e32 v102, 16, v41
	v_and_b32_e32 v103, 0xffff0000, v41
	v_lshlrev_b32_e32 v104, 16, v42
	v_and_b32_e32 v105, 0xffff0000, v42
	v_lshlrev_b32_e32 v106, 16, v43
	v_and_b32_e32 v107, 0xffff0000, v43
	v_add_f32_e32 v92, v92, v100
	v_add_f32_e32 v93, v93, v101
	v_add_f32_e32 v94, v94, v102
	v_add_f32_e32 v95, v95, v103
	v_add_f32_e32 v96, v96, v104
	v_add_f32_e32 v97, v97, v105
	v_add_f32_e32 v98, v98, v106
	v_add_f32_e32 v99, v99, v107
	v_fma_f32 v100, v92, v119, -v100
	v_fma_f32 v101, v93, v119, -v101
	v_fma_f32 v102, v94, v119, -v102
	v_fma_f32 v103, v95, v119, -v103
	v_fma_f32 v104, v96, v119, -v104
	v_fma_f32 v105, v97, v119, -v105
	v_fma_f32 v106, v98, v119, -v106
	v_fma_f32 v107, v99, v119, -v107
	v_cvt_pk_bf16_f32 v108, v100, v101
	v_cvt_pk_bf16_f32 v109, v102, v103
	v_cvt_pk_bf16_f32 v110, v104, v105
	v_cvt_pk_bf16_f32 v111, v106, v107
	global_store_dwordx4 v122, v[108:111], s[70:71]
	s_add_u32 s70, s70, 0x800
	s_addc_u32 s71, s71, 0
	s_add_u32 s8, s8, 1
	s_cmp_lt_u32 s8, 2
	s_cbranch_scc0 .Lpl_done
	s_add_u32 s4, s68, 0xfa000
	s_addc_u32 s5, s69, 0
	s_add_u32 s70, s66, 0x40000
	s_addc_u32 s71, s67, 0
	v_add_u32_e32 v120, 0x80, v120
	s_branch .Lpl_w4_pass
.Lpl_w8:
	s_sub_u32 s4, s68, 0xe000
	s_subb_u32 s5, s69, 0
	s_mov_b32 s70, s66
	s_mov_b32 s71, s67
	s_mov_b32 s8, 0
.Lpl_w8_pass:
	global_load_dwordx4 v[0:3], v121, s[4:5]
	s_add_u32 s4, s4, 0x2000
	s_addc_u32 s5, s5, 0
	global_load_dwordx4 v[4:7], v121, s[4:5]
	s_add_u32 s4, s4, 0x2000
	s_addc_u32 s5, s5, 0
	global_load_dwordx4 v[8:11], v121, s[4:5]
	s_add_u32 s4, s4, 0x2000
	s_addc_u32 s5, s5, 0
	global_load_dwordx4 v[12:15], v121, s[4:5]
	s_add_u32 s4, s4, 0x2000
	s_addc_u32 s5, s5, 0
	global_load_dwordx4 v[16:19], v121, s[4:5]
	s_add_u32 s4, s4, 0x2000
	s_addc_u32 s5, s5, 0
	global_load_dwordx4 v[20:23], v121, s[4:5]
	s_add_u32 s4, s4, 0x2000
	s_addc_u32 s5, s5, 0
	global_load_dwordx4 v[24:27], v121, s[4:5]
	s_add_u32 s4, s4, 0x2000
	s_addc_u32 s5, s5, 0
	global_load_dwordx4 v[28:31], v121, s[4:5]
	s_add_u32 s4, s4, 0x2000
	s_addc_u32 s5, s5, 0
	global_load_dwordx4 v[32:35], v121, s[4:5]
	s_add_u32 s4, s4, 0x2000
	s_addc_u32 s5, s5, 0
	global_load_dwordx4 v[36:39], v121, s[4:5]
	s_add_u32 s4, s4, 0x2000
	s_addc_u32 s5, s5, 0
	global_load_dwordx4 v[40:43], v121, s[4:5]
	s_add_u32 s4, s4, 0x2000
	s_addc_u32 s5, s5, 0
	global_load_dwordx4 v[44:47], v121, s[4:5]
	s_add_u32 s4, s4, 0x2000
	s_addc_u32 s5, s5, 0
	global_load_dwordx4 v[48:51], v121, s[4:5]
	s_add_u32 s4, s4, 0x2000
	s_addc_u32 s5, s5, 0
	global_load_dwordx4 v[52:55], v121, s[4:5]
	s_add_u32 s4, s4, 0x2000
	s_addc_u32 s5, s5, 0
	global_load_dwordx4 v[56:59], v121, s[4:5]
	s_add_u32 s4, s4, 0x2000
	s_addc_u32 s5, s5, 0
	s_waitcnt vmcnt(0)
	v_cmp_le_u32_e32 vcc, 7, v120
	s_nop 1
	v_cndmask_b32_e32 v0, 0, v0, vcc
	v_cndmask_b32_e32 v1, 0, v1, vcc
	v_cndmask_b32_e32 v2, 0, v2, vcc
	v_cndmask_b32_e32 v3, 0, v3, vcc
	v_cmp_le_u32_e32 vcc, 6, v120
	s_nop 1
	v_cndmask_b32_e32 v4, 0, v4, vcc
	v_cndmask_b32_e32 v5, 0, v5, vcc
	v_cndmask_b32_e32 v6, 0, v6, vcc
	v_cndmask_b32_e32 v7, 0, v7, vcc
	v_cmp_le_u32_e32 vcc, 5, v120
	s_nop 1
	v_cndmask_b32_e32 v8, 0, v8, vcc
	v_cndmask_b32_e32 v9, 0, v9, vcc
	v_cndmask_b32_e32 v10, 0, v10, vcc
	v_cndmask_b32_e32 v11, 0, v11, vcc
	v_cmp_le_u32_e32 vcc, 4, v120
	s_nop 1
	v_cndmask_b32_e32 v12, 0, v12, vcc
	v_cndmask_b32_e32 v13, 0, v13, vcc
	v_cndmask_b32_e32 v14, 0, v14, vcc
	v_cndmask_b32_e32 v15, 0, v15, vcc
	v_cmp_le_u32_e32 vcc, 3, v120
	s_nop 1
	v_cndmask_b32_e32 v16, 0, v16, vcc
	v_cndmask_b32_e32 v17, 0, v17, vcc
	v_cndmask_b32_e32 v18, 0, v18, vcc
	v_cndmask_b32_e32 v19, 0, v19, vcc
	v_cmp_le_u32_e32 vcc, 2, v120
	s_nop 1
	v_cndmask_b32_e32 v20, 0, v20, vcc
	v_cndmask_b32_e32 v21, 0, v21, vcc
	v_cndmask_b32_e32 v22, 0, v22, vcc
	v_cndmask_b32_e32 v23, 0, v23, vcc
	v_cmp_le_u32_e32 vcc, 1, v120
	s_nop 1
	v_cndmask_b32_e32 v24, 0, v24, vcc
	v_cndmask_b32_e32 v25, 0, v25, vcc
	v_cndmask_b32_e32 v26, 0, v26, vcc
	v_cndmask_b32_e32 v27, 0, v27, vcc
	v_lshlrev_b32_e32 v92, 16, v0
	v_and_b32_e32 v93, 0xffff0000, v0
	v_lshlrev_b32_e32 v94, 16, v1
	v_and_b32_e32 v95, 0xffff0000, v1
	v_lshlrev_b32_e32 v96, 16, v2
	v_and_b32_e32 v97, 0xffff0000, v2
	v_lshlrev_b32_e32 v98, 16, v3
	v_and_b32_e32 v99, 0xffff0000, v3
	v_lshlrev_b32_e32 v100, 16, v4
	v_and_b32_e32 v101, 0xffff0000, v4
	v_lshlrev_b32_e32 v102, 16, v5
	v_and_b32_e32 v103, 0xffff0000, v5
	v_lshlrev_b32_e32 v104, 16, v6
	v_and_b32_e32 v105, 0xffff0000, v6
	v_lshlrev_b32_e32 v106, 16, v7
	v_and_b32_e32 v107, 0xffff0000, v7
	v_add_f32_e32 v92, v92, v100
	v_add_f32_e32 v93, v93, v101
	v_add_f32_e32 v94, v94, v102
	v_add_f32_e32 v95, v95, v103
	v_add_f32_e32 v96, v96, v104
	v_add_f32_e32 v97, v97, v105
	v_add_f32_e32 v98, v98, v106
	v_add_f32_e32 v99, v99, v107
	v_lshlrev_b32_e32 v100, 16, v8
	v_and_b32_e32 v101, 0xffff0000, v8
	v_lshlrev_b32_e32 v102, 16, v9
	v_and_b32_e32 v103, 0xffff0000, v9
	v_lshlrev_b32_e32 v104, 16, v10
	v_and_b32_e32 v105, 0xffff0000, v10
	v_lshlrev_b32_e32 v106, 16, v11
	v_and_b32_e32 v107, 0xffff0000, v11
	v_add_f32_e32 v92, v92, v100
	v_add_f32_e32 v93, v93, v101
	v_add_f32_e32 v94, v94, v102
	v_add_f32_e32 v95, v95, v103
	v_add_f32_e32 v96, v96, v104
	v_add_f32_e32 v97, v97, v105
	v_add_f32_e32 v98, v98, v106
	v_add_f32_e32 v99, v99, v107
	v_lshlrev_b32_e32 v100, 16, v12
	v_and_b32_e32 v101, 0xffff0000, v12
	v_lshlrev_b32_e32 v102, 16, v13
	v_and_b32_e32 v103, 0xffff0000, v13
	v_lshlrev_b32_e32 v104, 16, v14
	v_and_b32_e32 v105, 0xffff0000, v14
	v_lshlrev_b32_e32 v106, 16, v15
	v_and_b32_e32 v107, 0xffff0000, v15
	v_add_f32_e32 v92, v92, v100
	v_add_f32_e32 v93, v93, v101
	v_add_f32_e32 v94, v94, v102
	v_add_f32_e32 v95, v95, v103
	v_add_f32_e32 v96, v96, v104
	v_add_f32_e32 v97, v97, v105
	v_add_f32_e32 v98, v98, v106
	v_add_f32_e32 v99, v99, v107
	v_lshlrev_b32_e32 v100, 16, v16
	v_and_b32_e32 v101, 0xffff0000, v16
	v_lshlrev_b32_e32 v102, 16, v17
	v_and_b32_e32 v103, 0xffff0000, v17
	v_lshlrev_b32_e32 v104, 16, v18
	v_and_b32_e32 v105, 0xffff0000, v18
	v_lshlrev_b32_e32 v106, 16, v19
	v_and_b32_e32 v107, 0xffff0000, v19
	v_add_f32_e32 v92, v92, v100
	v_add_f32_e32 v93, v93, v101
	v_add_f32_e32 v94, v94, v102
	v_add_f32_e32 v95, v95, v103
	v_add_f32_e32 v96, v96, v104
	v_add_f32_e32 v97, v97, v105
	v_add_f32_e32 v98, v98, v106
	v_add_f32_e32 v99, v99, v107
	v_lshlrev_b32_e32 v100, 16, v20
	v_and_b32_e32 v101, 0xffff0000, v20
	v_lshlrev_b32_e32 v102, 16, v21
	v_and_b32_e32 v103, 0xffff0000, v21
	v_lshlrev_b32_e32 v104, 16, v22
	v_and_b32_e32 v105, 0xffff0000, v22
	v_lshlrev_b32_e32 v106, 16, v23
	v_and_b32_e32 v107, 0xffff0000, v23
	v_add_f32_e32 v92, v92, v100
	v_add_f32_e32 v93, v93, v101
	v_add_f32_e32 v94, v94, v102
	v_add_f32_e32 v95, v95, v103
	v_add_f32_e32 v96, v96, v104
	v_add_f32_e32 v97, v97, v105
	v_add_f32_e32 v98, v98, v106
	v_add_f32_e32 v99, v99, v107
	v_lshlrev_b32_e32 v100, 16, v24
	v_and_b32_e32 v101, 0xffff0000, v24
	v_lshlrev_b32_e32 v102, 16, v25
	v_and_b32_e32 v103, 0xffff0000, v25
	v_lshlrev_b32_e32 v104, 16, v26
	v_and_b32_e32 v105, 0xffff0000, v26
	v_lshlrev_b32_e32 v106, 16, v27
	v_and_b32_e32 v107, 0xffff0000, v27
	v_add_f32_e32 v92, v92, v100
	v_add_f32_e32 v93, v93, v101
	v_add_f32_e32 v94, v94, v102
	v_add_f32_e32 v95, v95, v103
	v_add_f32_e32 v96, v96, v104
	v_add_f32_e32 v97, v97, v105
	v_add_f32_e32 v98, v98, v106
	v_add_f32_e32 v99, v99, v107
	v_add_u32_e32 v123, 1, v120
	v_min_u32_e32 v123, 8, v123
	v_cvt_f32_u32_e32 v112, v123
	v_div_scale_f32 v113, s[72:73], v112, v112, v118
	v_rcp_f32_e32 v114, v113
	v_div_scale_f32 v115, vcc, v118, v112, v118
	v_fma_f32 v116, -v113, v114, 1.0
	v_fmac_f32_e32 v114, v116, v114
	v_mul_f32_e32 v116, v115, v114
	v_fma_f32 v117, -v113, v116, v115
	v_fmac_f32_e32 v116, v117, v114
	v_fma_f32 v113, -v113, v116, v115
	v_div_fmas_f32 v113, v113, v114, v116
	v_div_fixup_f32 v119, v113, v112, v118
	v_lshlrev_b32_e32 v100, 16, v28
	v_and_b32_e32 v101, 0xffff0000, v28
	v_lshlrev_b32_e32 v102, 16, v29
	v_and_b32_e32 v103, 0xffff0000, v29
	v_lshlrev_b32_e32 v104, 16, v30
	v_and_b32_e32 v105, 0xffff0000, v30
	v_lshlrev_b32_e32 v106, 16, v31
	v_and_b32_e32 v107, 0xffff0000, v31
	v_add_f32_e32 v92, v92, v100
	v_add_f32_e32 v93, v93, v101
	v_add_f32_e32 v94, v94, v102
	v_add_f32_e32 v95, v95, v103
	v_add_f32_e32 v96, v96, v104
	v_add_f32_e32 v97, v97, v105
	v_add_f32_e32 v98, v98, v106
	v_add_f32_e32 v99, v99, v107
	v_fma_f32 v100, v92, v119, -v100
	v_fma_f32 v101, v93, v119, -v101
	v_fma_f32 v102, v94, v119, -v102
	v_fma_f32 v103, v95, v119, -v103
	v_fma_f32 v104, v96, v119, -v104
	v_fma_f32 v105, v97, v119, -v105
	v_fma_f32 v106, v98, v119, -v106
	v_fma_f32 v107, v99, v119, -v107
	v_cvt_pk_bf16_f32 v108, v100, v101
	v_cvt_pk_bf16_f32 v109, v102, v103
	v_cvt_pk_bf16_f32 v110, v104, v105
	v_cvt_pk_bf16_f32 v111, v106, v107
	global_store_dwordx4 v122, v[108:111], s[70:71]
	s_add_u32 s70, s70, 0x800
	s_addc_u32 s71, s71, 0
	v_lshlrev_b32_e32 v100, 16, v0
	v_and_b32_e32 v101, 0xffff0000, v0
	v_lshlrev_b32_e32 v102, 16, v1
	v_and_b32_e32 v103, 0xffff0000, v1
	v_lshlrev_b32_e32 v104, 16, v2
	v_and_b32_e32 v105, 0xffff0000, v2
	v_lshlrev_b32_e32 v106, 16, v3
	v_and_b32_e32 v107, 0xffff0000, v3
	v_sub_f32_e32 v92, v92, v100
	v_sub_f32_e32 v93, v93, v101
	v_sub_f32_e32 v94, v94, v102
	v_sub_f32_e32 v95, v95, v103
	v_sub_f32_e32 v96, v96, v104
	v_sub_f32_e32 v97, v97, v105
	v_sub_f32_e32 v98, v98, v106
	v_sub_f32_e32 v99, v99, v107
	v_add_u32_e32 v123, 2, v120
	v_min_u32_e32 v123, 8, v123
	v_cvt_f32_u32_e32 v112, v123
	v_div_scale_f32 v113, s[72:73], v112, v112, v118
	v_rcp_f32_e32 v114, v113
	v_div_scale_f32 v115, vcc, v118, v112, v118
	v_fma_f32 v116, -v113, v114, 1.0
	v_fmac_f32_e32 v114, v116, v114
	v_mul_f32_e32 v116, v115, v114
	v_fma_f32 v117, -v113, v116, v115
	v_fmac_f32_e32 v116, v117, v114
	v_fma_f32 v113, -v113, v116, v115
	v_div_fmas_f32 v113, v113, v114, v116
	v_div_fixup_f32 v119, v113, v112, v118
	v_lshlrev_b32_e32 v100, 16, v32
	v_and_b32_e32 v101, 0xffff0000, v32
	v_lshlrev_b32_e32 v102, 16, v33
	v_and_b32_e32 v103, 0xffff0000, v33
	v_lshlrev_b32_e32 v104, 16, v34
	v_and_b32_e32 v105, 0xffff0000, v34
	v_lshlrev_b32_e32 v106, 16, v35
	v_and_b32_e32 v107, 0xffff0000, v35
	v_add_f32_e32 v92, v92, v100
	v_add_f32_e32 v93, v93, v101
	v_add_f32_e32 v94, v94, v102
	v_add_f32_e32 v95, v95, v103
	v_add_f32_e32 v96, v96, v104
	v_add_f32_e32 v97, v97, v105
	v_add_f32_e32 v98, v98, v106
	v_add_f32_e32 v99, v99, v107
	v_fma_f32 v100, v92, v119, -v100
	v_fma_f32 v101, v93, v119, -v101
	v_fma_f32 v102, v94, v119, -v102
	v_fma_f32 v103, v95, v119, -v103
	v_fma_f32 v104, v96, v119, -v104
	v_fma_f32 v105, v97, v119, -v105
	v_fma_f32 v106, v98, v119, -v106
	v_fma_f32 v107, v99, v119, -v107
	v_cvt_pk_bf16_f32 v108, v100, v101
	v_cvt_pk_bf16_f32 v109, v102, v103
	v_cvt_pk_bf16_f32 v110, v104, v105
	v_cvt_pk_bf16_f32 v111, v106, v107
	global_store_dwordx4 v122, v[108:111], s[70:71]
	s_add_u32 s70, s70, 0x800
	s_addc_u32 s71, s71, 0
	v_lshlrev_b32_e32 v100, 16, v4
	v_and_b32_e32 v101, 0xffff0000, v4
	v_lshlrev_b32_e32 v102, 16, v5
	v_and_b32_e32 v103, 0xffff0000, v5
	v_lshlrev_b32_e32 v104, 16, v6
	v_and_b32_e32 v105, 0xffff0000, v6
	v_lshlrev_b32_e32 v106, 16, v7
	v_and_b32_e32 v107, 0xffff0000, v7
	v_sub_f32_e32 v92, v92, v100
	v_sub_f32_e32 v93, v93, v101
	v_sub_f32_e32 v94, v94, v102
	v_sub_f32_e32 v95, v95, v103
	v_sub_f32_e32 v96, v96, v104
	v_sub_f32_e32 v97, v97, v105
	v_sub_f32_e32 v98, v98, v106
	v_sub_f32_e32 v99, v99, v107
	v_add_u32_e32 v123, 3, v120
	v_min_u32_e32 v123, 8, v123
	v_cvt_f32_u32_e32 v112, v123
	v_div_scale_f32 v113, s[72:73], v112, v112, v118
	v_rcp_f32_e32 v114, v113
	v_div_scale_f32 v115, vcc, v118, v112, v118
	v_fma_f32 v116, -v113, v114, 1.0
	v_fmac_f32_e32 v114, v116, v114
	v_mul_f32_e32 v116, v115, v114
	v_fma_f32 v117, -v113, v116, v115
	v_fmac_f32_e32 v116, v117, v114
	v_fma_f32 v113, -v113, v116, v115
	v_div_fmas_f32 v113, v113, v114, v116
	v_div_fixup_f32 v119, v113, v112, v118
	v_lshlrev_b32_e32 v100, 16, v36
	v_and_b32_e32 v101, 0xffff0000, v36
	v_lshlrev_b32_e32 v102, 16, v37
	v_and_b32_e32 v103, 0xffff0000, v37
	v_lshlrev_b32_e32 v104, 16, v38
	v_and_b32_e32 v105, 0xffff0000, v38
	v_lshlrev_b32_e32 v106, 16, v39
	v_and_b32_e32 v107, 0xffff0000, v39
	v_add_f32_e32 v92, v92, v100
	v_add_f32_e32 v93, v93, v101
	v_add_f32_e32 v94, v94, v102
	v_add_f32_e32 v95, v95, v103
	v_add_f32_e32 v96, v96, v104
	v_add_f32_e32 v97, v97, v105
	v_add_f32_e32 v98, v98, v106
	v_add_f32_e32 v99, v99, v107
	v_fma_f32 v100, v92, v119, -v100
	v_fma_f32 v101, v93, v119, -v101
	v_fma_f32 v102, v94, v119, -v102
	v_fma_f32 v103, v95, v119, -v103
	v_fma_f32 v104, v96, v119, -v104
	v_fma_f32 v105, v97, v119, -v105
	v_fma_f32 v106, v98, v119, -v106
	v_fma_f32 v107, v99, v119, -v107
	v_cvt_pk_bf16_f32 v108, v100, v101
	v_cvt_pk_bf16_f32 v109, v102, v103
	v_cvt_pk_bf16_f32 v110, v104, v105
	v_cvt_pk_bf16_f32 v111, v106, v107
	global_store_dwordx4 v122, v[108:111], s[70:71]
	s_add_u32 s70, s70, 0x800
	s_addc_u32 s71, s71, 0
	v_lshlrev_b32_e32 v100, 16, v8
	v_and_b32_e32 v101, 0xffff0000, v8
	v_lshlrev_b32_e32 v102, 16, v9
	v_and_b32_e32 v103, 0xffff0000, v9
	v_lshlrev_b32_e32 v104, 16, v10
	v_and_b32_e32 v105, 0xffff0000, v10
	v_lshlrev_b32_e32 v106, 16, v11
	v_and_b32_e32 v107, 0xffff0000, v11
	v_sub_f32_e32 v92, v92, v100
	v_sub_f32_e32 v93, v93, v101
	v_sub_f32_e32 v94, v94, v102
	v_sub_f32_e32 v95, v95, v103
	v_sub_f32_e32 v96, v96, v104
	v_sub_f32_e32 v97, v97, v105
	v_sub_f32_e32 v98, v98, v106
	v_sub_f32_e32 v99, v99, v107
	v_add_u32_e32 v123, 4, v120
	v_min_u32_e32 v123, 8, v123
	v_cvt_f32_u32_e32 v112, v123
	v_div_scale_f32 v113, s[72:73], v112, v112, v118
	v_rcp_f32_e32 v114, v113
	v_div_scale_f32 v115, vcc, v118, v112, v118
	v_fma_f32 v116, -v113, v114, 1.0
	v_fmac_f32_e32 v114, v116, v114
	v_mul_f32_e32 v116, v115, v114
	v_fma_f32 v117, -v113, v116, v115
	v_fmac_f32_e32 v116, v117, v114
	v_fma_f32 v113, -v113, v116, v115
	v_div_fmas_f32 v113, v113, v114, v116
	v_div_fixup_f32 v119, v113, v112, v118
	v_lshlrev_b32_e32 v100, 16, v40
	v_and_b32_e32 v101, 0xffff0000, v40
	v_lshlrev_b32_e32 v102, 16, v41
	v_and_b32_e32 v103, 0xffff0000, v41
	v_lshlrev_b32_e32 v104, 16, v42
	v_and_b32_e32 v105, 0xffff0000, v42
	v_lshlrev_b32_e32 v106, 16, v43
	v_and_b32_e32 v107, 0xffff0000, v43
	v_add_f32_e32 v92, v92, v100
	v_add_f32_e32 v93, v93, v101
	v_add_f32_e32 v94, v94, v102
	v_add_f32_e32 v95, v95, v103
	v_add_f32_e32 v96, v96, v104
	v_add_f32_e32 v97, v97, v105
	v_add_f32_e32 v98, v98, v106
	v_add_f32_e32 v99, v99, v107
	v_fma_f32 v100, v92, v119, -v100
	v_fma_f32 v101, v93, v119, -v101
	v_fma_f32 v102, v94, v119, -v102
	v_fma_f32 v103, v95, v119, -v103
	v_fma_f32 v104, v96, v119, -v104
	v_fma_f32 v105, v97, v119, -v105
	v_fma_f32 v106, v98, v119, -v106
	v_fma_f32 v107, v99, v119, -v107
	v_cvt_pk_bf16_f32 v108, v100, v101
	v_cvt_pk_bf16_f32 v109, v102, v103
	v_cvt_pk_bf16_f32 v110, v104, v105
	v_cvt_pk_bf16_f32 v111, v106, v107
	global_store_dwordx4 v122, v[108:111], s[70:71]
	s_add_u32 s70, s70, 0x800
	s_addc_u32 s71, s71, 0
	v_lshlrev_b32_e32 v100, 16, v12
	v_and_b32_e32 v101, 0xffff0000, v12
	v_lshlrev_b32_e32 v102, 16, v13
	v_and_b32_e32 v103, 0xffff0000, v13
	v_lshlrev_b32_e32 v104, 16, v14
	v_and_b32_e32 v105, 0xffff0000, v14
	v_lshlrev_b32_e32 v106, 16, v15
	v_and_b32_e32 v107, 0xffff0000, v15
	v_sub_f32_e32 v92, v92, v100
	v_sub_f32_e32 v93, v93, v101
	v_sub_f32_e32 v94, v94, v102
	v_sub_f32_e32 v95, v95, v103
	v_sub_f32_e32 v96, v96, v104
	v_sub_f32_e32 v97, v97, v105
	v_sub_f32_e32 v98, v98, v106
	v_sub_f32_e32 v99, v99, v107
	v_add_u32_e32 v123, 5, v120
	v_min_u32_e32 v123, 8, v123
	v_cvt_f32_u32_e32 v112, v123
	v_div_scale_f32 v113, s[72:73], v112, v112, v118
	v_rcp_f32_e32 v114, v113
	v_div_scale_f32 v115, vcc, v118, v112, v118
	v_fma_f32 v116, -v113, v114, 1.0
	v_fmac_f32_e32 v114, v116, v114
	v_mul_f32_e32 v116, v115, v114
	v_fma_f32 v117, -v113, v116, v115
	v_fmac_f32_e32 v116, v117, v114
	v_fma_f32 v113, -v113, v116, v115
	v_div_fmas_f32 v113, v113, v114, v116
	v_div_fixup_f32 v119, v113, v112, v118
	v_lshlrev_b32_e32 v100, 16, v44
	v_and_b32_e32 v101, 0xffff0000, v44
	v_lshlrev_b32_e32 v102, 16, v45
	v_and_b32_e32 v103, 0xffff0000, v45
	v_lshlrev_b32_e32 v104, 16, v46
	v_and_b32_e32 v105, 0xffff0000, v46
	v_lshlrev_b32_e32 v106, 16, v47
	v_and_b32_e32 v107, 0xffff0000, v47
	v_add_f32_e32 v92, v92, v100
	v_add_f32_e32 v93, v93, v101
	v_add_f32_e32 v94, v94, v102
	v_add_f32_e32 v95, v95, v103
	v_add_f32_e32 v96, v96, v104
	v_add_f32_e32 v97, v97, v105
	v_add_f32_e32 v98, v98, v106
	v_add_f32_e32 v99, v99, v107
	v_fma_f32 v100, v92, v119, -v100
	v_fma_f32 v101, v93, v119, -v101
	v_fma_f32 v102, v94, v119, -v102
	v_fma_f32 v103, v95, v119, -v103
	v_fma_f32 v104, v96, v119, -v104
	v_fma_f32 v105, v97, v119, -v105
	v_fma_f32 v106, v98, v119, -v106
	v_fma_f32 v107, v99, v119, -v107
	v_cvt_pk_bf16_f32 v108, v100, v101
	v_cvt_pk_bf16_f32 v109, v102, v103
	v_cvt_pk_bf16_f32 v110, v104, v105
	v_cvt_pk_bf16_f32 v111, v106, v107
	global_store_dwordx4 v122, v[108:111], s[70:71]
	s_add_u32 s70, s70, 0x800
	s_addc_u32 s71, s71, 0
	v_lshlrev_b32_e32 v100, 16, v16
	v_and_b32_e32 v101, 0xffff0000, v16
	v_lshlrev_b32_e32 v102, 16, v17
	v_and_b32_e32 v103, 0xffff0000, v17
	v_lshlrev_b32_e32 v104, 16, v18
	v_and_b32_e32 v105, 0xffff0000, v18
	v_lshlrev_b32_e32 v106, 16, v19
	v_and_b32_e32 v107, 0xffff0000, v19
	v_sub_f32_e32 v92, v92, v100
	v_sub_f32_e32 v93, v93, v101
	v_sub_f32_e32 v94, v94, v102
	v_sub_f32_e32 v95, v95, v103
	v_sub_f32_e32 v96, v96, v104
	v_sub_f32_e32 v97, v97, v105
	v_sub_f32_e32 v98, v98, v106
	v_sub_f32_e32 v99, v99, v107
	v_add_u32_e32 v123, 6, v120
	v_min_u32_e32 v123, 8, v123
	v_cvt_f32_u32_e32 v112, v123
	v_div_scale_f32 v113, s[72:73], v112, v112, v118
	v_rcp_f32_e32 v114, v113
	v_div_scale_f32 v115, vcc, v118, v112, v118
	v_fma_f32 v116, -v113, v114, 1.0
	v_fmac_f32_e32 v114, v116, v114
	v_mul_f32_e32 v116, v115, v114
	v_fma_f32 v117, -v113, v116, v115
	v_fmac_f32_e32 v116, v117, v114
	v_fma_f32 v113, -v113, v116, v115
	v_div_fmas_f32 v113, v113, v114, v116
	v_div_fixup_f32 v119, v113, v112, v118
	v_lshlrev_b32_e32 v100, 16, v48
	v_and_b32_e32 v101, 0xffff0000, v48
	v_lshlrev_b32_e32 v102, 16, v49
	v_and_b32_e32 v103, 0xffff0000, v49
	v_lshlrev_b32_e32 v104, 16, v50
	v_and_b32_e32 v105, 0xffff0000, v50
	v_lshlrev_b32_e32 v106, 16, v51
	v_and_b32_e32 v107, 0xffff0000, v51
	v_add_f32_e32 v92, v92, v100
	v_add_f32_e32 v93, v93, v101
	v_add_f32_e32 v94, v94, v102
	v_add_f32_e32 v95, v95, v103
	v_add_f32_e32 v96, v96, v104
	v_add_f32_e32 v97, v97, v105
	v_add_f32_e32 v98, v98, v106
	v_add_f32_e32 v99, v99, v107
	v_fma_f32 v100, v92, v119, -v100
	v_fma_f32 v101, v93, v119, -v101
	v_fma_f32 v102, v94, v119, -v102
	v_fma_f32 v103, v95, v119, -v103
	v_fma_f32 v104, v96, v119, -v104
	v_fma_f32 v105, v97, v119, -v105
	v_fma_f32 v106, v98, v119, -v106
	v_fma_f32 v107, v99, v119, -v107
	v_cvt_pk_bf16_f32 v108, v100, v101
	v_cvt_pk_bf16_f32 v109, v102, v103
	v_cvt_pk_bf16_f32 v110, v104, v105
	v_cvt_pk_bf16_f32 v111, v106, v107
	global_store_dwordx4 v122, v[108:111], s[70:71]
	s_add_u32 s70, s70, 0x800
	s_addc_u32 s71, s71, 0
	v_lshlrev_b32_e32 v100, 16, v20
	v_and_b32_e32 v101, 0xffff0000, v20
	v_lshlrev_b32_e32 v102, 16, v21
	v_and_b32_e32 v103, 0xffff0000, v21
	v_lshlrev_b32_e32 v104, 16, v22
	v_and_b32_e32 v105, 0xffff0000, v22
	v_lshlrev_b32_e32 v106, 16, v23
	v_and_b32_e32 v107, 0xffff0000, v23
	v_sub_f32_e32 v92, v92, v100
	v_sub_f32_e32 v93, v93, v101
	v_sub_f32_e32 v94, v94, v102
	v_sub_f32_e32 v95, v95, v103
	v_sub_f32_e32 v96, v96, v104
	v_sub_f32_e32 v97, v97, v105
	v_sub_f32_e32 v98, v98, v106
	v_sub_f32_e32 v99, v99, v107
	v_add_u32_e32 v123, 7, v120
	v_min_u32_e32 v123, 8, v123
	v_cvt_f32_u32_e32 v112, v123
	v_div_scale_f32 v113, s[72:73], v112, v112, v118
	v_rcp_f32_e32 v114, v113
	v_div_scale_f32 v115, vcc, v118, v112, v118
	v_fma_f32 v116, -v113, v114, 1.0
	v_fmac_f32_e32 v114, v116, v114
	v_mul_f32_e32 v116, v115, v114
	v_fma_f32 v117, -v113, v116, v115
	v_fmac_f32_e32 v116, v117, v114
	v_fma_f32 v113, -v113, v116, v115
	v_div_fmas_f32 v113, v113, v114, v116
	v_div_fixup_f32 v119, v113, v112, v118
	v_lshlrev_b32_e32 v100, 16, v52
	v_and_b32_e32 v101, 0xffff0000, v52
	v_lshlrev_b32_e32 v102, 16, v53
	v_and_b32_e32 v103, 0xffff0000, v53
	v_lshlrev_b32_e32 v104, 16, v54
	v_and_b32_e32 v105, 0xffff0000, v54
	v_lshlrev_b32_e32 v106, 16, v55
	v_and_b32_e32 v107, 0xffff0000, v55
	v_add_f32_e32 v92, v92, v100
	v_add_f32_e32 v93, v93, v101
	v_add_f32_e32 v94, v94, v102
	v_add_f32_e32 v95, v95, v103
	v_add_f32_e32 v96, v96, v104
	v_add_f32_e32 v97, v97, v105
	v_add_f32_e32 v98, v98, v106
	v_add_f32_e32 v99, v99, v107
	v_fma_f32 v100, v92, v119, -v100
	v_fma_f32 v101, v93, v119, -v101
	v_fma_f32 v102, v94, v119, -v102
	v_fma_f32 v103, v95, v119, -v103
	v_fma_f32 v104, v96, v119, -v104
	v_fma_f32 v105, v97, v119, -v105
	v_fma_f32 v106, v98, v119, -v106
	v_fma_f32 v107, v99, v119, -v107
	v_cvt_pk_bf16_f32 v108, v100, v101
	v_cvt_pk_bf16_f32 v109, v102, v103
	v_cvt_pk_bf16_f32 v110, v104, v105
	v_cvt_pk_bf16_f32 v111, v106, v107
	global_store_dwordx4 v122, v[108:111], s[70:71]
	s_add_u32 s70, s70, 0x800
	s_addc_u32 s71, s71, 0
	v_lshlrev_b32_e32 v100, 16, v24
	v_and_b32_e32 v101, 0xffff0000, v24
	v_lshlrev_b32_e32 v102, 16, v25
	v_and_b32_e32 v103, 0xffff0000, v25
	v_lshlrev_b32_e32 v104, 16, v26
	v_and_b32_e32 v105, 0xffff0000, v26
	v_lshlrev_b32_e32 v106, 16, v27
	v_and_b32_e32 v107, 0xffff0000, v27
	v_sub_f32_e32 v92, v92, v100
	v_sub_f32_e32 v93, v93, v101
	v_sub_f32_e32 v94, v94, v102
	v_sub_f32_e32 v95, v95, v103
	v_sub_f32_e32 v96, v96, v104
	v_sub_f32_e32 v97, v97, v105
	v_sub_f32_e32 v98, v98, v106
	v_sub_f32_e32 v99, v99, v107
	v_mov_b32_e32 v119, 0x3e000000
	v_lshlrev_b32_e32 v100, 16, v56
	v_and_b32_e32 v101, 0xffff0000, v56
	v_lshlrev_b32_e32 v102, 16, v57
	v_and_b32_e32 v103, 0xffff0000, v57
	v_lshlrev_b32_e32 v104, 16, v58
	v_and_b32_e32 v105, 0xffff0000, v58
	v_lshlrev_b32_e32 v106, 16, v59
	v_and_b32_e32 v107, 0xffff0000, v59
	v_add_f32_e32 v92, v92, v100
	v_add_f32_e32 v93, v93, v101
	v_add_f32_e32 v94, v94, v102
	v_add_f32_e32 v95, v95, v103
	v_add_f32_e32 v96, v96, v104
	v_add_f32_e32 v97, v97, v105
	v_add_f32_e32 v98, v98, v106
	v_add_f32_e32 v99, v99, v107
	v_fma_f32 v100, v92, v119, -v100
	v_fma_f32 v101, v93, v119, -v101
	v_fma_f32 v102, v94, v119, -v102
	v_fma_f32 v103, v95, v119, -v103
	v_fma_f32 v104, v96, v119, -v104
	v_fma_f32 v105, v97, v119, -v105
	v_fma_f32 v106, v98, v119, -v106
	v_fma_f32 v107, v99, v119, -v107
	v_cvt_pk_bf16_f32 v108, v100, v101
	v_cvt_pk_bf16_f32 v109, v102, v103
	v_cvt_pk_bf16_f32 v110, v104, v105
	v_cvt_pk_bf16_f32 v111, v106, v107
	global_store_dwordx4 v122, v[108:111], s[70:71]
	s_add_u32 s70, s70, 0x800
	s_addc_u32 s71, s71, 0
	s_add_u32 s8, s8, 1
	s_cmp_lt_u32 s8, 2
	s_cbranch_scc0 .Lpl_done
	s_add_u32 s4, s68, 0xf2000
	s_addc_u32 s5, s69, 0
	s_add_u32 s70, s66, 0x40000
	s_addc_u32 s71, s67, 0
	v_add_u32_e32 v120, 0x80, v120
	s_branch .Lpl_w8_pass
.Lpl_w16:
	s_sub_u32 s4, s68, 0x1e000
	s_subb_u32 s5, s69, 0
	s_mov_b32 s70, s66
	s_mov_b32 s71, s67
	s_mov_b32 s8, 0
.Lpl_w16_pass:
	global_load_dwordx4 v[0:3], v121, s[4:5]
	s_add_u32 s4, s4, 0x2000
	s_addc_u32 s5, s5, 0
	global_load_dwordx4 v[4:7], v121, s[4:5]
	s_add_u32 s4, s4, 0x2000
	s_addc_u32 s5, s5, 0
	global_load_dwordx4 v[8:11], v121, s[4:5]
	s_add_u32 s4, s4, 0x2000
	s_addc_u32 s5, s5, 0
	global_load_dwordx4 v[12:15], v121, s[4:5]
	s_add_u32 s4, s4, 0x2000
	s_addc_u32 s5, s5, 0
	global_load_dwordx4 v[16:19], v121, s[4:5]
	s_add_u32 s4, s4, 0x2000
	s_addc_u32 s5, s5, 0
	global_load_dwordx4 v[20:23], v121, s[4:5]
	s_add_u32 s4, s4, 0x2000
	s_addc_u32 s5, s5, 0
	global_load_dwordx4 v[24:27], v121, s[4:5]
	s_add_u32 s4, s4, 0x2000
	s_addc_u32 s5, s5, 0
	global_load_dwordx4 v[28:31], v121, s[4:5]
	s_add_u32 s4, s4, 0x2000
	s_addc_u32 s5, s5, 0
	global_load_dwordx4 v[32:35], v121, s[4:5]
	s_add_u32 s4, s4, 0x2000
	s_addc_u32 s5, s5, 0
	global_load_dwordx4 v[36:39], v121, s[4:5]
	s_add_u32 s4, s4, 0x2000
	s_addc_u32 s5, s5, 0
	global_load_dwordx4 v[40:43], v121, s[4:5]
	s_add_u32 s4, s4, 0x2000
	s_addc_u32 s5, s5, 0
	global_load_dwordx4 v[44:47], v121, s[4:5]
	s_add_u32 s4, s4, 0x2000
	s_addc_u32 s5, s5, 0
	global_load_dwordx4 v[48:51], v121, s[4:5]
	s_add_u32 s4, s4, 0x2000
	s_addc_u32 s5, s5, 0
	global_load_dwordx4 v[52:55], v121, s[4:5]
	s_add_u32 s4, s4, 0x2000
	s_addc_u32 s5, s5, 0
	global_load_dwordx4 v[56:59], v121, s[4:5]
	s_add_u32 s4, s4, 0x2000
	s_addc_u32 s5, s5, 0
	global_load_dwordx4 v[60:63], v121, s[4:5]
	s_add_u32 s4, s4, 0x2000
	s_addc_u32 s5, s5, 0
	global_load_dwordx4 v[64:67], v121, s[4:5]
	s_add_u32 s4, s4, 0x2000
	s_addc_u32 s5, s5, 0
	global_load_dwordx4 v[68:71], v121, s[4:5]
	s_add_u32 s4, s4, 0x2000
	s_addc_u32 s5, s5, 0
	global_load_dwordx4 v[72:75], v121, s[4:5]
	s_add_u32 s4, s4, 0x2000
	s_addc_u32 s5, s5, 0
	global_load_dwordx4 v[76:79], v121, s[4:5]
	s_add_u32 s4, s4, 0x2000
	s_addc_u32 s5, s5, 0
	global_load_dwordx4 v[80:83], v121, s[4:5]
	s_add_u32 s4, s4, 0x2000
	s_addc_u32 s5, s5, 0
	global_load_dwordx4 v[84:87], v121, s[4:5]
	s_add_u32 s4, s4, 0x2000
	s_addc_u32 s5, s5, 0
	global_load_dwordx4 v[88:91], v121, s[4:5]
	s_add_u32 s4, s4, 0x2000
	s_addc_u32 s5, s5, 0
	s_waitcnt vmcnt(0)
	v_cmp_le_u32_e32 vcc, 15, v120
	s_nop 1
	v_cndmask_b32_e32 v0, 0, v0, vcc
	v_cndmask_b32_e32 v1, 0, v1, vcc
	v_cndmask_b32_e32 v2, 0, v2, vcc
	v_cndmask_b32_e32 v3, 0, v3, vcc
	v_cmp_le_u32_e32 vcc, 14, v120
	s_nop 1
	v_cndmask_b32_e32 v4, 0, v4, vcc
	v_cndmask_b32_e32 v5, 0, v5, vcc
	v_cndmask_b32_e32 v6, 0, v6, vcc
	v_cndmask_b32_e32 v7, 0, v7, vcc
	v_cmp_le_u32_e32 vcc, 13, v120
	s_nop 1
	v_cndmask_b32_e32 v8, 0, v8, vcc
	v_cndmask_b32_e32 v9, 0, v9, vcc
	v_cndmask_b32_e32 v10, 0, v10, vcc
	v_cndmask_b32_e32 v11, 0, v11, vcc
	v_cmp_le_u32_e32 vcc, 12, v120
	s_nop 1
	v_cndmask_b32_e32 v12, 0, v12, vcc
	v_cndmask_b32_e32 v13, 0, v13, vcc
	v_cndmask_b32_e32 v14, 0, v14, vcc
	v_cndmask_b32_e32 v15, 0, v15, vcc
	v_cmp_le_u32_e32 vcc, 11, v120
	s_nop 1
	v_cndmask_b32_e32 v16, 0, v16, vcc
	v_cndmask_b32_e32 v17, 0, v17, vcc
	v_cndmask_b32_e32 v18, 0, v18, vcc
	v_cndmask_b32_e32 v19, 0, v19, vcc
	v_cmp_le_u32_e32 vcc, 10, v120
	s_nop 1
	v_cndmask_b32_e32 v20, 0, v20, vcc
	v_cndmask_b32_e32 v21, 0, v21, vcc
	v_cndmask_b32_e32 v22, 0, v22, vcc
	v_cndmask_b32_e32 v23, 0, v23, vcc
	v_cmp_le_u32_e32 vcc, 9, v120
	s_nop 1
	v_cndmask_b32_e32 v24, 0, v24, vcc
	v_cndmask_b32_e32 v25, 0, v25, vcc
	v_cndmask_b32_e32 v26, 0, v26, vcc
	v_cndmask_b32_e32 v27, 0, v27, vcc
	v_cmp_le_u32_e32 vcc, 8, v120
	s_nop 1
	v_cndmask_b32_e32 v28, 0, v28, vcc
	v_cndmask_b32_e32 v29, 0, v29, vcc
	v_cndmask_b32_e32 v30, 0, v30, vcc
	v_cndmask_b32_e32 v31, 0, v31, vcc
	v_cmp_le_u32_e32 vcc, 7, v120
	s_nop 1
	v_cndmask_b32_e32 v32, 0, v32, vcc
	v_cndmask_b32_e32 v33, 0, v33, vcc
	v_cndmask_b32_e32 v34, 0, v34, vcc
	v_cndmask_b32_e32 v35, 0, v35, vcc
	v_cmp_le_u32_e32 vcc, 6, v120
	s_nop 1
	v_cndmask_b32_e32 v36, 0, v36, vcc
	v_cndmask_b32_e32 v37, 0, v37, vcc
	v_cndmask_b32_e32 v38, 0, v38, vcc
	v_cndmask_b32_e32 v39, 0, v39, vcc
	v_cmp_le_u32_e32 vcc, 5, v120
	s_nop 1
	v_cndmask_b32_e32 v40, 0, v40, vcc
	v_cndmask_b32_e32 v41, 0, v41, vcc
	v_cndmask_b32_e32 v42, 0, v42, vcc
	v_cndmask_b32_e32 v43, 0, v43, vcc
	v_cmp_le_u32_e32 vcc, 4, v120
	s_nop 1
	v_cndmask_b32_e32 v44, 0, v44, vcc
	v_cndmask_b32_e32 v45, 0, v45, vcc
	v_cndmask_b32_e32 v46, 0, v46, vcc
	v_cndmask_b32_e32 v47, 0, v47, vcc
	v_cmp_le_u32_e32 vcc, 3, v120
	s_nop 1
	v_cndmask_b32_e32 v48, 0, v48, vcc
	v_cndmask_b32_e32 v49, 0, v49, vcc
	v_cndmask_b32_e32 v50, 0, v50, vcc
	v_cndmask_b32_e32 v51, 0, v51, vcc
	v_cmp_le_u32_e32 vcc, 2, v120
	s_nop 1
	v_cndmask_b32_e32 v52, 0, v52, vcc
	v_cndmask_b32_e32 v53, 0, v53, vcc
	v_cndmask_b32_e32 v54, 0, v54, vcc
	v_cndmask_b32_e32 v55, 0, v55, vcc
	v_cmp_le_u32_e32 vcc, 1, v120
	s_nop 1
	v_cndmask_b32_e32 v56, 0, v56, vcc
	v_cndmask_b32_e32 v57, 0, v57, vcc
	v_cndmask_b32_e32 v58, 0, v58, vcc
	v_cndmask_b32_e32 v59, 0, v59, vcc
	v_lshlrev_b32_e32 v92, 16, v0
	v_and_b32_e32 v93, 0xffff0000, v0
	v_lshlrev_b32_e32 v94, 16, v1
	v_and_b32_e32 v95, 0xffff0000, v1
	v_lshlrev_b32_e32 v96, 16, v2
	v_and_b32_e32 v97, 0xffff0000, v2
	v_lshlrev_b32_e32 v98, 16, v3
	v_and_b32_e32 v99, 0xffff0000, v3
	v_lshlrev_b32_e32 v100, 16, v4
	v_and_b32_e32 v101, 0xffff0000, v4
	v_lshlrev_b32_e32 v102, 16, v5
	v_and_b32_e32 v103, 0xffff0000, v5
	v_lshlrev_b32_e32 v104, 16, v6
	v_and_b32_e32 v105, 0xffff0000, v6
	v_lshlrev_b32_e32 v106, 16, v7
	v_and_b32_e32 v107, 0xffff0000, v7
	v_add_f32_e32 v92, v92, v100
	v_add_f32_e32 v93, v93, v101
	v_add_f32_e32 v94, v94, v102
	v_add_f32_e32 v95, v95, v103
	v_add_f32_e32 v96, v96, v104
	v_add_f32_e32 v97, v97, v105
	v_add_f32_e32 v98, v98, v106
	v_add_f32_e32 v99, v99, v107
	v_lshlrev_b32_e32 v100, 16, v8
	v_and_b32_e32 v101, 0xffff0000, v8
	v_lshlrev_b32_e32 v102, 16, v9
	v_and_b32_e32 v103, 0xffff0000, v9
	v_lshlrev_b32_e32 v104, 16, v10
	v_and_b32_e32 v105, 0xffff0000, v10
	v_lshlrev_b32_e32 v106, 16, v11
	v_and_b32_e32 v107, 0xffff0000, v11
	v_add_f32_e32 v92, v92, v100
	v_add_f32_e32 v93, v93, v101
	v_add_f32_e32 v94, v94, v102
	v_add_f32_e32 v95, v95, v103
	v_add_f32_e32 v96, v96, v104
	v_add_f32_e32 v97, v97, v105
	v_add_f32_e32 v98, v98, v106
	v_add_f32_e32 v99, v99, v107
	v_lshlrev_b32_e32 v100, 16, v12
	v_and_b32_e32 v101, 0xffff0000, v12
	v_lshlrev_b32_e32 v102, 16, v13
	v_and_b32_e32 v103, 0xffff0000, v13
	v_lshlrev_b32_e32 v104, 16, v14
	v_and_b32_e32 v105, 0xffff0000, v14
	v_lshlrev_b32_e32 v106, 16, v15
	v_and_b32_e32 v107, 0xffff0000, v15
	v_add_f32_e32 v92, v92, v100
	v_add_f32_e32 v93, v93, v101
	v_add_f32_e32 v94, v94, v102
	v_add_f32_e32 v95, v95, v103
	v_add_f32_e32 v96, v96, v104
	v_add_f32_e32 v97, v97, v105
	v_add_f32_e32 v98, v98, v106
	v_add_f32_e32 v99, v99, v107
	v_lshlrev_b32_e32 v100, 16, v16
	v_and_b32_e32 v101, 0xffff0000, v16
	v_lshlrev_b32_e32 v102, 16, v17
	v_and_b32_e32 v103, 0xffff0000, v17
	v_lshlrev_b32_e32 v104, 16, v18
	v_and_b32_e32 v105, 0xffff0000, v18
	v_lshlrev_b32_e32 v106, 16, v19
	v_and_b32_e32 v107, 0xffff0000, v19
	v_add_f32_e32 v92, v92, v100
	v_add_f32_e32 v93, v93, v101
	v_add_f32_e32 v94, v94, v102
	v_add_f32_e32 v95, v95, v103
	v_add_f32_e32 v96, v96, v104
	v_add_f32_e32 v97, v97, v105
	v_add_f32_e32 v98, v98, v106
	v_add_f32_e32 v99, v99, v107
	v_lshlrev_b32_e32 v100, 16, v20
	v_and_b32_e32 v101, 0xffff0000, v20
	v_lshlrev_b32_e32 v102, 16, v21
	v_and_b32_e32 v103, 0xffff0000, v21
	v_lshlrev_b32_e32 v104, 16, v22
	v_and_b32_e32 v105, 0xffff0000, v22
	v_lshlrev_b32_e32 v106, 16, v23
	v_and_b32_e32 v107, 0xffff0000, v23
	v_add_f32_e32 v92, v92, v100
	v_add_f32_e32 v93, v93, v101
	v_add_f32_e32 v94, v94, v102
	v_add_f32_e32 v95, v95, v103
	v_add_f32_e32 v96, v96, v104
	v_add_f32_e32 v97, v97, v105
	v_add_f32_e32 v98, v98, v106
	v_add_f32_e32 v99, v99, v107
	v_lshlrev_b32_e32 v100, 16, v24
	v_and_b32_e32 v101, 0xffff0000, v24
	v_lshlrev_b32_e32 v102, 16, v25
	v_and_b32_e32 v103, 0xffff0000, v25
	v_lshlrev_b32_e32 v104, 16, v26
	v_and_b32_e32 v105, 0xffff0000, v26
	v_lshlrev_b32_e32 v106, 16, v27
	v_and_b32_e32 v107, 0xffff0000, v27
	v_add_f32_e32 v92, v92, v100
	v_add_f32_e32 v93, v93, v101
	v_add_f32_e32 v94, v94, v102
	v_add_f32_e32 v95, v95, v103
	v_add_f32_e32 v96, v96, v104
	v_add_f32_e32 v97, v97, v105
	v_add_f32_e32 v98, v98, v106
	v_add_f32_e32 v99, v99, v107
	v_lshlrev_b32_e32 v100, 16, v28
	v_and_b32_e32 v101, 0xffff0000, v28
	v_lshlrev_b32_e32 v102, 16, v29
	v_and_b32_e32 v103, 0xffff0000, v29
	v_lshlrev_b32_e32 v104, 16, v30
	v_and_b32_e32 v105, 0xffff0000, v30
	v_lshlrev_b32_e32 v106, 16, v31
	v_and_b32_e32 v107, 0xffff0000, v31
	v_add_f32_e32 v92, v92, v100
	v_add_f32_e32 v93, v93, v101
	v_add_f32_e32 v94, v94, v102
	v_add_f32_e32 v95, v95, v103
	v_add_f32_e32 v96, v96, v104
	v_add_f32_e32 v97, v97, v105
	v_add_f32_e32 v98, v98, v106
	v_add_f32_e32 v99, v99, v107
	v_lshlrev_b32_e32 v100, 16, v32
	v_and_b32_e32 v101, 0xffff0000, v32
	v_lshlrev_b32_e32 v102, 16, v33
	v_and_b32_e32 v103, 0xffff0000, v33
	v_lshlrev_b32_e32 v104, 16, v34
	v_and_b32_e32 v105, 0xffff0000, v34
	v_lshlrev_b32_e32 v106, 16, v35
	v_and_b32_e32 v107, 0xffff0000, v35
	v_add_f32_e32 v92, v92, v100
	v_add_f32_e32 v93, v93, v101
	v_add_f32_e32 v94, v94, v102
	v_add_f32_e32 v95, v95, v103
	v_add_f32_e32 v96, v96, v104
	v_add_f32_e32 v97, v97, v105
	v_add_f32_e32 v98, v98, v106
	v_add_f32_e32 v99, v99, v107
	v_lshlrev_b32_e32 v100, 16, v36
	v_and_b32_e32 v101, 0xffff0000, v36
	v_lshlrev_b32_e32 v102, 16, v37
	v_and_b32_e32 v103, 0xffff0000, v37
	v_lshlrev_b32_e32 v104, 16, v38
	v_and_b32_e32 v105, 0xffff0000, v38
	v_lshlrev_b32_e32 v106, 16, v39
	v_and_b32_e32 v107, 0xffff0000, v39
	v_add_f32_e32 v92, v92, v100
	v_add_f32_e32 v93, v93, v101
	v_add_f32_e32 v94, v94, v102
	v_add_f32_e32 v95, v95, v103
	v_add_f32_e32 v96, v96, v104
	v_add_f32_e32 v97, v97, v105
	v_add_f32_e32 v98, v98, v106
	v_add_f32_e32 v99, v99, v107
	v_lshlrev_b32_e32 v100, 16, v40
	v_and_b32_e32 v101, 0xffff0000, v40
	v_lshlrev_b32_e32 v102, 16, v41
	v_and_b32_e32 v103, 0xffff0000, v41
	v_lshlrev_b32_e32 v104, 16, v42
	v_and_b32_e32 v105, 0xffff0000, v42
	v_lshlrev_b32_e32 v106, 16, v43
	v_and_b32_e32 v107, 0xffff0000, v43
	v_add_f32_e32 v92, v92, v100
	v_add_f32_e32 v93, v93, v101
	v_add_f32_e32 v94, v94, v102
	v_add_f32_e32 v95, v95, v103
	v_add_f32_e32 v96, v96, v104
	v_add_f32_e32 v97, v97, v105
	v_add_f32_e32 v98, v98, v106
	v_add_f32_e32 v99, v99, v107
	v_lshlrev_b32_e32 v100, 16, v44
	v_and_b32_e32 v101, 0xffff0000, v44
	v_lshlrev_b32_e32 v102, 16, v45
	v_and_b32_e32 v103, 0xffff0000, v45
	v_lshlrev_b32_e32 v104, 16, v46
	v_and_b32_e32 v105, 0xffff0000, v46
	v_lshlrev_b32_e32 v106, 16, v47
	v_and_b32_e32 v107, 0xffff0000, v47
	v_add_f32_e32 v92, v92, v100
	v_add_f32_e32 v93, v93, v101
	v_add_f32_e32 v94, v94, v102
	v_add_f32_e32 v95, v95, v103
	v_add_f32_e32 v96, v96, v104
	v_add_f32_e32 v97, v97, v105
	v_add_f32_e32 v98, v98, v106
	v_add_f32_e32 v99, v99, v107
	v_lshlrev_b32_e32 v100, 16, v48
	v_and_b32_e32 v101, 0xffff0000, v48
	v_lshlrev_b32_e32 v102, 16, v49
	v_and_b32_e32 v103, 0xffff0000, v49
	v_lshlrev_b32_e32 v104, 16, v50
	v_and_b32_e32 v105, 0xffff0000, v50
	v_lshlrev_b32_e32 v106, 16, v51
	v_and_b32_e32 v107, 0xffff0000, v51
	v_add_f32_e32 v92, v92, v100
	v_add_f32_e32 v93, v93, v101
	v_add_f32_e32 v94, v94, v102
	v_add_f32_e32 v95, v95, v103
	v_add_f32_e32 v96, v96, v104
	v_add_f32_e32 v97, v97, v105
	v_add_f32_e32 v98, v98, v106
	v_add_f32_e32 v99, v99, v107
	v_lshlrev_b32_e32 v100, 16, v52
	v_and_b32_e32 v101, 0xffff0000, v52
	v_lshlrev_b32_e32 v102, 16, v53
	v_and_b32_e32 v103, 0xffff0000, v53
	v_lshlrev_b32_e32 v104, 16, v54
	v_and_b32_e32 v105, 0xffff0000, v54
	v_lshlrev_b32_e32 v106, 16, v55
	v_and_b32_e32 v107, 0xffff0000, v55
	v_add_f32_e32 v92, v92, v100
	v_add_f32_e32 v93, v93, v101
	v_add_f32_e32 v94, v94, v102
	v_add_f32_e32 v95, v95, v103
	v_add_f32_e32 v96, v96, v104
	v_add_f32_e32 v97, v97, v105
	v_add_f32_e32 v98, v98, v106
	v_add_f32_e32 v99, v99, v107
	v_lshlrev_b32_e32 v100, 16, v56
	v_and_b32_e32 v101, 0xffff0000, v56
	v_lshlrev_b32_e32 v102, 16, v57
	v_and_b32_e32 v103, 0xffff0000, v57
	v_lshlrev_b32_e32 v104, 16, v58
	v_and_b32_e32 v105, 0xffff0000, v58
	v_lshlrev_b32_e32 v106, 16, v59
	v_and_b32_e32 v107, 0xffff0000, v59
	v_add_f32_e32 v92, v92, v100
	v_add_f32_e32 v93, v93, v101
	v_add_f32_e32 v94, v94, v102
	v_add_f32_e32 v95, v95, v103
	v_add_f32_e32 v96, v96, v104
	v_add_f32_e32 v97, v97, v105
	v_add_f32_e32 v98, v98, v106
	v_add_f32_e32 v99, v99, v107
	v_add_u32_e32 v123, 1, v120
	v_min_u32_e32 v123, 16, v123
	v_cvt_f32_u32_e32 v112, v123
	v_div_scale_f32 v113, s[72:73], v112, v112, v118
	v_rcp_f32_e32 v114, v113
	v_div_scale_f32 v115, vcc, v118, v112, v118
	v_fma_f32 v116, -v113, v114, 1.0
	v_fmac_f32_e32 v114, v116, v114
	v_mul_f32_e32 v116, v115, v114
	v_fma_f32 v117, -v113, v116, v115
	v_fmac_f32_e32 v116, v117, v114
	v_fma_f32 v113, -v113, v116, v115
	v_div_fmas_f32 v113, v113, v114, v116
	v_div_fixup_f32 v119, v113, v112, v118
	v_lshlrev_b32_e32 v100, 16, v60
	v_and_b32_e32 v101, 0xffff0000, v60
	v_lshlrev_b32_e32 v102, 16, v61
	v_and_b32_e32 v103, 0xffff0000, v61
	v_lshlrev_b32_e32 v104, 16, v62
	v_and_b32_e32 v105, 0xffff0000, v62
	v_lshlrev_b32_e32 v106, 16, v63
	v_and_b32_e32 v107, 0xffff0000, v63
	v_add_f32_e32 v92, v92, v100
	v_add_f32_e32 v93, v93, v101
	v_add_f32_e32 v94, v94, v102
	v_add_f32_e32 v95, v95, v103
	v_add_f32_e32 v96, v96, v104
	v_add_f32_e32 v97, v97, v105
	v_add_f32_e32 v98, v98, v106
	v_add_f32_e32 v99, v99, v107
	v_fma_f32 v100, v92, v119, -v100
	v_fma_f32 v101, v93, v119, -v101
	v_fma_f32 v102, v94, v119, -v102
	v_fma_f32 v103, v95, v119, -v103
	v_fma_f32 v104, v96, v119, -v104
	v_fma_f32 v105, v97, v119, -v105
	v_fma_f32 v106, v98, v119, -v106
	v_fma_f32 v107, v99, v119, -v107
	v_cvt_pk_bf16_f32 v108, v100, v101
	v_cvt_pk_bf16_f32 v109, v102, v103
	v_cvt_pk_bf16_f32 v110, v104, v105
	v_cvt_pk_bf16_f32 v111, v106, v107
	global_store_dwordx4 v122, v[108:111], s[70:71]
	s_add_u32 s70, s70, 0x800
	s_addc_u32 s71, s71, 0
	v_lshlrev_b32_e32 v100, 16, v0
	v_and_b32_e32 v101, 0xffff0000, v0
	v_lshlrev_b32_e32 v102, 16, v1
	v_and_b32_e32 v103, 0xffff0000, v1
	v_lshlrev_b32_e32 v104, 16, v2
	v_and_b32_e32 v105, 0xffff0000, v2
	v_lshlrev_b32_e32 v106, 16, v3
	v_and_b32_e32 v107, 0xffff0000, v3
	v_sub_f32_e32 v92, v92, v100
	v_sub_f32_e32 v93, v93, v101
	v_sub_f32_e32 v94, v94, v102
	v_sub_f32_e32 v95, v95, v103
	v_sub_f32_e32 v96, v96, v104
	v_sub_f32_e32 v97, v97, v105
	v_sub_f32_e32 v98, v98, v106
	v_sub_f32_e32 v99, v99, v107
	v_add_u32_e32 v123, 2, v120
	v_min_u32_e32 v123, 16, v123
	v_cvt_f32_u32_e32 v112, v123
	v_div_scale_f32 v113, s[72:73], v112, v112, v118
	v_rcp_f32_e32 v114, v113
	v_div_scale_f32 v115, vcc, v118, v112, v118
	v_fma_f32 v116, -v113, v114, 1.0
	v_fmac_f32_e32 v114, v116, v114
	v_mul_f32_e32 v116, v115, v114
	v_fma_f32 v117, -v113, v116, v115
	v_fmac_f32_e32 v116, v117, v114
	v_fma_f32 v113, -v113, v116, v115
	v_div_fmas_f32 v113, v113, v114, v116
	v_div_fixup_f32 v119, v113, v112, v118
	v_lshlrev_b32_e32 v100, 16, v64
	v_and_b32_e32 v101, 0xffff0000, v64
	v_lshlrev_b32_e32 v102, 16, v65
	v_and_b32_e32 v103, 0xffff0000, v65
	v_lshlrev_b32_e32 v104, 16, v66
	v_and_b32_e32 v105, 0xffff0000, v66
	v_lshlrev_b32_e32 v106, 16, v67
	v_and_b32_e32 v107, 0xffff0000, v67
	v_add_f32_e32 v92, v92, v100
	v_add_f32_e32 v93, v93, v101
	v_add_f32_e32 v94, v94, v102
	v_add_f32_e32 v95, v95, v103
	v_add_f32_e32 v96, v96, v104
	v_add_f32_e32 v97, v97, v105
	v_add_f32_e32 v98, v98, v106
	v_add_f32_e32 v99, v99, v107
	v_fma_f32 v100, v92, v119, -v100
	v_fma_f32 v101, v93, v119, -v101
	v_fma_f32 v102, v94, v119, -v102
	v_fma_f32 v103, v95, v119, -v103
	v_fma_f32 v104, v96, v119, -v104
	v_fma_f32 v105, v97, v119, -v105
	v_fma_f32 v106, v98, v119, -v106
	v_fma_f32 v107, v99, v119, -v107
	v_cvt_pk_bf16_f32 v108, v100, v101
	v_cvt_pk_bf16_f32 v109, v102, v103
	v_cvt_pk_bf16_f32 v110, v104, v105
	v_cvt_pk_bf16_f32 v111, v106, v107
	global_store_dwordx4 v122, v[108:111], s[70:71]
	s_add_u32 s70, s70, 0x800
	s_addc_u32 s71, s71, 0
	v_lshlrev_b32_e32 v100, 16, v4
	v_and_b32_e32 v101, 0xffff0000, v4
	v_lshlrev_b32_e32 v102, 16, v5
	v_and_b32_e32 v103, 0xffff0000, v5
	v_lshlrev_b32_e32 v104, 16, v6
	v_and_b32_e32 v105, 0xffff0000, v6
	v_lshlrev_b32_e32 v106, 16, v7
	v_and_b32_e32 v107, 0xffff0000, v7
	v_sub_f32_e32 v92, v92, v100
	v_sub_f32_e32 v93, v93, v101
	v_sub_f32_e32 v94, v94, v102
	v_sub_f32_e32 v95, v95, v103
	v_sub_f32_e32 v96, v96, v104
	v_sub_f32_e32 v97, v97, v105
	v_sub_f32_e32 v98, v98, v106
	v_sub_f32_e32 v99, v99, v107
	v_add_u32_e32 v123, 3, v120
	v_min_u32_e32 v123, 16, v123
	v_cvt_f32_u32_e32 v112, v123
	v_div_scale_f32 v113, s[72:73], v112, v112, v118
	v_rcp_f32_e32 v114, v113
	v_div_scale_f32 v115, vcc, v118, v112, v118
	v_fma_f32 v116, -v113, v114, 1.0
	v_fmac_f32_e32 v114, v116, v114
	v_mul_f32_e32 v116, v115, v114
	v_fma_f32 v117, -v113, v116, v115
	v_fmac_f32_e32 v116, v117, v114
	v_fma_f32 v113, -v113, v116, v115
	v_div_fmas_f32 v113, v113, v114, v116
	v_div_fixup_f32 v119, v113, v112, v118
	v_lshlrev_b32_e32 v100, 16, v68
	v_and_b32_e32 v101, 0xffff0000, v68
	v_lshlrev_b32_e32 v102, 16, v69
	v_and_b32_e32 v103, 0xffff0000, v69
	v_lshlrev_b32_e32 v104, 16, v70
	v_and_b32_e32 v105, 0xffff0000, v70
	v_lshlrev_b32_e32 v106, 16, v71
	v_and_b32_e32 v107, 0xffff0000, v71
	v_add_f32_e32 v92, v92, v100
	v_add_f32_e32 v93, v93, v101
	v_add_f32_e32 v94, v94, v102
	v_add_f32_e32 v95, v95, v103
	v_add_f32_e32 v96, v96, v104
	v_add_f32_e32 v97, v97, v105
	v_add_f32_e32 v98, v98, v106
	v_add_f32_e32 v99, v99, v107
	v_fma_f32 v100, v92, v119, -v100
	v_fma_f32 v101, v93, v119, -v101
	v_fma_f32 v102, v94, v119, -v102
	v_fma_f32 v103, v95, v119, -v103
	v_fma_f32 v104, v96, v119, -v104
	v_fma_f32 v105, v97, v119, -v105
	v_fma_f32 v106, v98, v119, -v106
	v_fma_f32 v107, v99, v119, -v107
	v_cvt_pk_bf16_f32 v108, v100, v101
	v_cvt_pk_bf16_f32 v109, v102, v103
	v_cvt_pk_bf16_f32 v110, v104, v105
	v_cvt_pk_bf16_f32 v111, v106, v107
	global_store_dwordx4 v122, v[108:111], s[70:71]
	s_add_u32 s70, s70, 0x800
	s_addc_u32 s71, s71, 0
	v_lshlrev_b32_e32 v100, 16, v8
	v_and_b32_e32 v101, 0xffff0000, v8
	v_lshlrev_b32_e32 v102, 16, v9
	v_and_b32_e32 v103, 0xffff0000, v9
	v_lshlrev_b32_e32 v104, 16, v10
	v_and_b32_e32 v105, 0xffff0000, v10
	v_lshlrev_b32_e32 v106, 16, v11
	v_and_b32_e32 v107, 0xffff0000, v11
	v_sub_f32_e32 v92, v92, v100
	v_sub_f32_e32 v93, v93, v101
	v_sub_f32_e32 v94, v94, v102
	v_sub_f32_e32 v95, v95, v103
	v_sub_f32_e32 v96, v96, v104
	v_sub_f32_e32 v97, v97, v105
	v_sub_f32_e32 v98, v98, v106
	v_sub_f32_e32 v99, v99, v107
	v_add_u32_e32 v123, 4, v120
	v_min_u32_e32 v123, 16, v123
	v_cvt_f32_u32_e32 v112, v123
	v_div_scale_f32 v113, s[72:73], v112, v112, v118
	v_rcp_f32_e32 v114, v113
	v_div_scale_f32 v115, vcc, v118, v112, v118
	v_fma_f32 v116, -v113, v114, 1.0
	v_fmac_f32_e32 v114, v116, v114
	v_mul_f32_e32 v116, v115, v114
	v_fma_f32 v117, -v113, v116, v115
	v_fmac_f32_e32 v116, v117, v114
	v_fma_f32 v113, -v113, v116, v115
	v_div_fmas_f32 v113, v113, v114, v116
	v_div_fixup_f32 v119, v113, v112, v118
	v_lshlrev_b32_e32 v100, 16, v72
	v_and_b32_e32 v101, 0xffff0000, v72
	v_lshlrev_b32_e32 v102, 16, v73
	v_and_b32_e32 v103, 0xffff0000, v73
	v_lshlrev_b32_e32 v104, 16, v74
	v_and_b32_e32 v105, 0xffff0000, v74
	v_lshlrev_b32_e32 v106, 16, v75
	v_and_b32_e32 v107, 0xffff0000, v75
	v_add_f32_e32 v92, v92, v100
	v_add_f32_e32 v93, v93, v101
	v_add_f32_e32 v94, v94, v102
	v_add_f32_e32 v95, v95, v103
	v_add_f32_e32 v96, v96, v104
	v_add_f32_e32 v97, v97, v105
	v_add_f32_e32 v98, v98, v106
	v_add_f32_e32 v99, v99, v107
	v_fma_f32 v100, v92, v119, -v100
	v_fma_f32 v101, v93, v119, -v101
	v_fma_f32 v102, v94, v119, -v102
	v_fma_f32 v103, v95, v119, -v103
	v_fma_f32 v104, v96, v119, -v104
	v_fma_f32 v105, v97, v119, -v105
	v_fma_f32 v106, v98, v119, -v106
	v_fma_f32 v107, v99, v119, -v107
	v_cvt_pk_bf16_f32 v108, v100, v101
	v_cvt_pk_bf16_f32 v109, v102, v103
	v_cvt_pk_bf16_f32 v110, v104, v105
	v_cvt_pk_bf16_f32 v111, v106, v107
	global_store_dwordx4 v122, v[108:111], s[70:71]
	s_add_u32 s70, s70, 0x800
	s_addc_u32 s71, s71, 0
	v_lshlrev_b32_e32 v100, 16, v12
	v_and_b32_e32 v101, 0xffff0000, v12
	v_lshlrev_b32_e32 v102, 16, v13
	v_and_b32_e32 v103, 0xffff0000, v13
	v_lshlrev_b32_e32 v104, 16, v14
	v_and_b32_e32 v105, 0xffff0000, v14
	v_lshlrev_b32_e32 v106, 16, v15
	v_and_b32_e32 v107, 0xffff0000, v15
	v_sub_f32_e32 v92, v92, v100
	v_sub_f32_e32 v93, v93, v101
	v_sub_f32_e32 v94, v94, v102
	v_sub_f32_e32 v95, v95, v103
	v_sub_f32_e32 v96, v96, v104
	v_sub_f32_e32 v97, v97, v105
	v_sub_f32_e32 v98, v98, v106
	v_sub_f32_e32 v99, v99, v107
	v_add_u32_e32 v123, 5, v120
	v_min_u32_e32 v123, 16, v123
	v_cvt_f32_u32_e32 v112, v123
	v_div_scale_f32 v113, s[72:73], v112, v112, v118
	v_rcp_f32_e32 v114, v113
	v_div_scale_f32 v115, vcc, v118, v112, v118
	v_fma_f32 v116, -v113, v114, 1.0
	v_fmac_f32_e32 v114, v116, v114
	v_mul_f32_e32 v116, v115, v114
	v_fma_f32 v117, -v113, v116, v115
	v_fmac_f32_e32 v116, v117, v114
	v_fma_f32 v113, -v113, v116, v115
	v_div_fmas_f32 v113, v113, v114, v116
	v_div_fixup_f32 v119, v113, v112, v118
	v_lshlrev_b32_e32 v100, 16, v76
	v_and_b32_e32 v101, 0xffff0000, v76
	v_lshlrev_b32_e32 v102, 16, v77
	v_and_b32_e32 v103, 0xffff0000, v77
	v_lshlrev_b32_e32 v104, 16, v78
	v_and_b32_e32 v105, 0xffff0000, v78
	v_lshlrev_b32_e32 v106, 16, v79
	v_and_b32_e32 v107, 0xffff0000, v79
	v_add_f32_e32 v92, v92, v100
	v_add_f32_e32 v93, v93, v101
	v_add_f32_e32 v94, v94, v102
	v_add_f32_e32 v95, v95, v103
	v_add_f32_e32 v96, v96, v104
	v_add_f32_e32 v97, v97, v105
	v_add_f32_e32 v98, v98, v106
	v_add_f32_e32 v99, v99, v107
	v_fma_f32 v100, v92, v119, -v100
	v_fma_f32 v101, v93, v119, -v101
	v_fma_f32 v102, v94, v119, -v102
	v_fma_f32 v103, v95, v119, -v103
	v_fma_f32 v104, v96, v119, -v104
	v_fma_f32 v105, v97, v119, -v105
	v_fma_f32 v106, v98, v119, -v106
	v_fma_f32 v107, v99, v119, -v107
	v_cvt_pk_bf16_f32 v108, v100, v101
	v_cvt_pk_bf16_f32 v109, v102, v103
	v_cvt_pk_bf16_f32 v110, v104, v105
	v_cvt_pk_bf16_f32 v111, v106, v107
	global_store_dwordx4 v122, v[108:111], s[70:71]
	s_add_u32 s70, s70, 0x800
	s_addc_u32 s71, s71, 0
	v_lshlrev_b32_e32 v100, 16, v16
	v_and_b32_e32 v101, 0xffff0000, v16
	v_lshlrev_b32_e32 v102, 16, v17
	v_and_b32_e32 v103, 0xffff0000, v17
	v_lshlrev_b32_e32 v104, 16, v18
	v_and_b32_e32 v105, 0xffff0000, v18
	v_lshlrev_b32_e32 v106, 16, v19
	v_and_b32_e32 v107, 0xffff0000, v19
	v_sub_f32_e32 v92, v92, v100
	v_sub_f32_e32 v93, v93, v101
	v_sub_f32_e32 v94, v94, v102
	v_sub_f32_e32 v95, v95, v103
	v_sub_f32_e32 v96, v96, v104
	v_sub_f32_e32 v97, v97, v105
	v_sub_f32_e32 v98, v98, v106
	v_sub_f32_e32 v99, v99, v107
	v_add_u32_e32 v123, 6, v120
	v_min_u32_e32 v123, 16, v123
	v_cvt_f32_u32_e32 v112, v123
	v_div_scale_f32 v113, s[72:73], v112, v112, v118
	v_rcp_f32_e32 v114, v113
	v_div_scale_f32 v115, vcc, v118, v112, v118
	v_fma_f32 v116, -v113, v114, 1.0
	v_fmac_f32_e32 v114, v116, v114
	v_mul_f32_e32 v116, v115, v114
	v_fma_f32 v117, -v113, v116, v115
	v_fmac_f32_e32 v116, v117, v114
	v_fma_f32 v113, -v113, v116, v115
	v_div_fmas_f32 v113, v113, v114, v116
	v_div_fixup_f32 v119, v113, v112, v118
	v_lshlrev_b32_e32 v100, 16, v80
	v_and_b32_e32 v101, 0xffff0000, v80
	v_lshlrev_b32_e32 v102, 16, v81
	v_and_b32_e32 v103, 0xffff0000, v81
	v_lshlrev_b32_e32 v104, 16, v82
	v_and_b32_e32 v105, 0xffff0000, v82
	v_lshlrev_b32_e32 v106, 16, v83
	v_and_b32_e32 v107, 0xffff0000, v83
	v_add_f32_e32 v92, v92, v100
	v_add_f32_e32 v93, v93, v101
	v_add_f32_e32 v94, v94, v102
	v_add_f32_e32 v95, v95, v103
	v_add_f32_e32 v96, v96, v104
	v_add_f32_e32 v97, v97, v105
	v_add_f32_e32 v98, v98, v106
	v_add_f32_e32 v99, v99, v107
	v_fma_f32 v100, v92, v119, -v100
	v_fma_f32 v101, v93, v119, -v101
	v_fma_f32 v102, v94, v119, -v102
	v_fma_f32 v103, v95, v119, -v103
	v_fma_f32 v104, v96, v119, -v104
	v_fma_f32 v105, v97, v119, -v105
	v_fma_f32 v106, v98, v119, -v106
	v_fma_f32 v107, v99, v119, -v107
	v_cvt_pk_bf16_f32 v108, v100, v101
	v_cvt_pk_bf16_f32 v109, v102, v103
	v_cvt_pk_bf16_f32 v110, v104, v105
	v_cvt_pk_bf16_f32 v111, v106, v107
	global_store_dwordx4 v122, v[108:111], s[70:71]
	s_add_u32 s70, s70, 0x800
	s_addc_u32 s71, s71, 0
	v_lshlrev_b32_e32 v100, 16, v20
	v_and_b32_e32 v101, 0xffff0000, v20
	v_lshlrev_b32_e32 v102, 16, v21
	v_and_b32_e32 v103, 0xffff0000, v21
	v_lshlrev_b32_e32 v104, 16, v22
	v_and_b32_e32 v105, 0xffff0000, v22
	v_lshlrev_b32_e32 v106, 16, v23
	v_and_b32_e32 v107, 0xffff0000, v23
	v_sub_f32_e32 v92, v92, v100
	v_sub_f32_e32 v93, v93, v101
	v_sub_f32_e32 v94, v94, v102
	v_sub_f32_e32 v95, v95, v103
	v_sub_f32_e32 v96, v96, v104
	v_sub_f32_e32 v97, v97, v105
	v_sub_f32_e32 v98, v98, v106
	v_sub_f32_e32 v99, v99, v107
	v_add_u32_e32 v123, 7, v120
	v_min_u32_e32 v123, 16, v123
	v_cvt_f32_u32_e32 v112, v123
	v_div_scale_f32 v113, s[72:73], v112, v112, v118
	v_rcp_f32_e32 v114, v113
	v_div_scale_f32 v115, vcc, v118, v112, v118
	v_fma_f32 v116, -v113, v114, 1.0
	v_fmac_f32_e32 v114, v116, v114
	v_mul_f32_e32 v116, v115, v114
	v_fma_f32 v117, -v113, v116, v115
	v_fmac_f32_e32 v116, v117, v114
	v_fma_f32 v113, -v113, v116, v115
	v_div_fmas_f32 v113, v113, v114, v116
	v_div_fixup_f32 v119, v113, v112, v118
	v_lshlrev_b32_e32 v100, 16, v84
	v_and_b32_e32 v101, 0xffff0000, v84
	v_lshlrev_b32_e32 v102, 16, v85
	v_and_b32_e32 v103, 0xffff0000, v85
	v_lshlrev_b32_e32 v104, 16, v86
	v_and_b32_e32 v105, 0xffff0000, v86
	v_lshlrev_b32_e32 v106, 16, v87
	v_and_b32_e32 v107, 0xffff0000, v87
	v_add_f32_e32 v92, v92, v100
	v_add_f32_e32 v93, v93, v101
	v_add_f32_e32 v94, v94, v102
	v_add_f32_e32 v95, v95, v103
	v_add_f32_e32 v96, v96, v104
	v_add_f32_e32 v97, v97, v105
	v_add_f32_e32 v98, v98, v106
	v_add_f32_e32 v99, v99, v107
	v_fma_f32 v100, v92, v119, -v100
	v_fma_f32 v101, v93, v119, -v101
	v_fma_f32 v102, v94, v119, -v102
	v_fma_f32 v103, v95, v119, -v103
	v_fma_f32 v104, v96, v119, -v104
	v_fma_f32 v105, v97, v119, -v105
	v_fma_f32 v106, v98, v119, -v106
	v_fma_f32 v107, v99, v119, -v107
	v_cvt_pk_bf16_f32 v108, v100, v101
	v_cvt_pk_bf16_f32 v109, v102, v103
	v_cvt_pk_bf16_f32 v110, v104, v105
	v_cvt_pk_bf16_f32 v111, v106, v107
	global_store_dwordx4 v122, v[108:111], s[70:71]
	s_add_u32 s70, s70, 0x800
	s_addc_u32 s71, s71, 0
	v_lshlrev_b32_e32 v100, 16, v24
	v_and_b32_e32 v101, 0xffff0000, v24
	v_lshlrev_b32_e32 v102, 16, v25
	v_and_b32_e32 v103, 0xffff0000, v25
	v_lshlrev_b32_e32 v104, 16, v26
	v_and_b32_e32 v105, 0xffff0000, v26
	v_lshlrev_b32_e32 v106, 16, v27
	v_and_b32_e32 v107, 0xffff0000, v27
	v_sub_f32_e32 v92, v92, v100
	v_sub_f32_e32 v93, v93, v101
	v_sub_f32_e32 v94, v94, v102
	v_sub_f32_e32 v95, v95, v103
	v_sub_f32_e32 v96, v96, v104
	v_sub_f32_e32 v97, v97, v105
	v_sub_f32_e32 v98, v98, v106
	v_sub_f32_e32 v99, v99, v107
	v_add_u32_e32 v123, 8, v120
	v_min_u32_e32 v123, 16, v123
	v_cvt_f32_u32_e32 v112, v123
	v_div_scale_f32 v113, s[72:73], v112, v112, v118
	v_rcp_f32_e32 v114, v113
	v_div_scale_f32 v115, vcc, v118, v112, v118
	v_fma_f32 v116, -v113, v114, 1.0
	v_fmac_f32_e32 v114, v116, v114
	v_mul_f32_e32 v116, v115, v114
	v_fma_f32 v117, -v113, v116, v115
	v_fmac_f32_e32 v116, v117, v114
	v_fma_f32 v113, -v113, v116, v115
	v_div_fmas_f32 v113, v113, v114, v116
	v_div_fixup_f32 v119, v113, v112, v118
	v_lshlrev_b32_e32 v100, 16, v88
	v_and_b32_e32 v101, 0xffff0000, v88
	v_lshlrev_b32_e32 v102, 16, v89
	v_and_b32_e32 v103, 0xffff0000, v89
	v_lshlrev_b32_e32 v104, 16, v90
	v_and_b32_e32 v105, 0xffff0000, v90
	v_lshlrev_b32_e32 v106, 16, v91
	v_and_b32_e32 v107, 0xffff0000, v91
	v_add_f32_e32 v92, v92, v100
	v_add_f32_e32 v93, v93, v101
	v_add_f32_e32 v94, v94, v102
	v_add_f32_e32 v95, v95, v103
	v_add_f32_e32 v96, v96, v104
	v_add_f32_e32 v97, v97, v105
	v_add_f32_e32 v98, v98, v106
	v_add_f32_e32 v99, v99, v107
	v_fma_f32 v100, v92, v119, -v100
	v_fma_f32 v101, v93, v119, -v101
	v_fma_f32 v102, v94, v119, -v102
	v_fma_f32 v103, v95, v119, -v103
	v_fma_f32 v104, v96, v119, -v104
	v_fma_f32 v105, v97, v119, -v105
	v_fma_f32 v106, v98, v119, -v106
	v_fma_f32 v107, v99, v119, -v107
	v_cvt_pk_bf16_f32 v108, v100, v101
	v_cvt_pk_bf16_f32 v109, v102, v103
	v_cvt_pk_bf16_f32 v110, v104, v105
	v_cvt_pk_bf16_f32 v111, v106, v107
	global_store_dwordx4 v122, v[108:111], s[70:71]
	s_add_u32 s70, s70, 0x800
	s_addc_u32 s71, s71, 0
	s_add_u32 s8, s8, 1
	s_cmp_lt_u32 s8, 2
	s_cbranch_scc0 .Lpl_done
	s_add_u32 s4, s68, 0xe2000
	s_addc_u32 s5, s69, 0
	s_add_u32 s70, s66, 0x40000
	s_addc_u32 s71, s67, 0
	v_add_u32_e32 v120, 0x80, v120
	s_branch .Lpl_w16_pass
.Lpl_done:
	s_lshl_b32 s64, s62, 8
	s_branch .LBB0_603

.LBB0_613:
	s_andn2_b64 vcc, exec, s[6:7]
	s_cbranch_vccnz .LBB0_618
	s_cmpk_gt_i32 s17, 0x7f
	s_cbranch_scc1 .LBB0_618
	v_and_b32_e32 v110, 63, v252
	v_lshrrev_b32_e32 v0, 6, v252
	v_writelane_b32 v111, s16, 0
	v_writelane_b32 v111, s17, 1
	v_writelane_b32 v111, s18, 2
	v_writelane_b32 v111, s19, 3
	v_writelane_b32 v111, s20, 4
	v_writelane_b32 v111, s21, 5
	v_writelane_b32 v111, s22, 6
	v_writelane_b32 v111, s23, 7
	v_writelane_b32 v111, s24, 8
	v_writelane_b32 v111, s25, 9
	v_writelane_b32 v111, s26, 10
	v_writelane_b32 v111, s27, 11
	v_readfirstlane_b32 s0, v0
	s_mul_i32 s1, s0, 0x4100
	s_lshl_b32 s16, s17, 3
	s_add_u32 s16, s16, s0
	s_cmp_lt_u32 s16, 0xb00
	s_cbranch_scc0 .Lcv_wdl_skip
	v_lshrrev_b32_e32 v0, 4, v110
	v_and_b32_e32 v1, 15, v110
	v_and_b32_e32 v2, 7, v110
	v_lshrrev_b32_e32 v3, 3, v110
	v_mul_u32_u24_e32 v64, 0x2000, v0
	v_lshl_add_u32 v64, v1, 4, v64
	v_mul_u32_u24_e32 v65, 0x104, v0
	v_lshl_add_u32 v65, v1, 4, v65
	v_add_u32_e32 v65, s1, v65
	v_mul_u32_u24_e32 v66, 0x820, v2
	v_lshl_add_u32 v66, v3, 2, v66
	v_add_u32_e32 v66, s1, v66
	v_add_u32_e32 v67, 0x410, v66
	v_mul_u32_u24_e32 v68, 0x2c00, v3
	v_lshl_add_u32 v68, v2, 4, v68
	v_mov_b32_e32 v4, 0x23fa0
	ds_read_b64 v[0:1], v4
	s_waitcnt lgkmcnt(0)
	v_readfirstlane_b32 s18, v0
	v_readfirstlane_b32 s19, v1
	s_add_u32 s26, s54, 0x4800000
	s_addc_u32 s27, s55, 0
	s_nop 4
	s_lshr_b32 s98, s16, 5
	s_and_b32 s99, s16, 31
	s_lshl_b32 s0, s98, 19
	s_lshl_b32 s100, s99, 8
	s_add_u32 s0, s0, s100
	s_add_u32 s4, s18, s0
	s_addc_u32 s5, s19, 0
	s_mul_i32 s0, s99, 0xb0000
	s_lshl_b32 s100, s98, 7
	s_add_u32 s0, s0, s100
	s_add_u32 s24, s26, s0
	s_addc_u32 s25, s27, 0
	global_load_dwordx4 v[0:3], v64, s[4:5] nt
	s_add_u32 s4, s4, 0x8000
	s_addc_u32 s5, s5, 0
	global_load_dwordx4 v[4:7], v64, s[4:5] nt
	s_add_u32 s4, s4, 0x8000
	s_addc_u32 s5, s5, 0
	global_load_dwordx4 v[8:11], v64, s[4:5] nt
	s_add_u32 s4, s4, 0x8000
	s_addc_u32 s5, s5, 0
	global_load_dwordx4 v[12:15], v64, s[4:5] nt
	s_add_u32 s4, s4, 0x8000
	s_addc_u32 s5, s5, 0
	global_load_dwordx4 v[16:19], v64, s[4:5] nt
	s_add_u32 s4, s4, 0x8000
	s_addc_u32 s5, s5, 0
	global_load_dwordx4 v[20:23], v64, s[4:5] nt
	s_add_u32 s4, s4, 0x8000
	s_addc_u32 s5, s5, 0
	global_load_dwordx4 v[24:27], v64, s[4:5] nt
	s_add_u32 s4, s4, 0x8000
	s_addc_u32 s5, s5, 0
	global_load_dwordx4 v[28:31], v64, s[4:5] nt
	s_add_u32 s4, s4, 0x8000
	s_addc_u32 s5, s5, 0
	global_load_dwordx4 v[32:35], v64, s[4:5] nt
	s_add_u32 s4, s4, 0x8000
	s_addc_u32 s5, s5, 0
	global_load_dwordx4 v[36:39], v64, s[4:5] nt
	s_add_u32 s4, s4, 0x8000
	s_addc_u32 s5, s5, 0
	global_load_dwordx4 v[40:43], v64, s[4:5] nt
	s_add_u32 s4, s4, 0x8000
	s_addc_u32 s5, s5, 0
	global_load_dwordx4 v[44:47], v64, s[4:5] nt
	s_add_u32 s4, s4, 0x8000
	s_addc_u32 s5, s5, 0
	global_load_dwordx4 v[48:51], v64, s[4:5] nt
	s_add_u32 s4, s4, 0x8000
	s_addc_u32 s5, s5, 0
	global_load_dwordx4 v[52:55], v64, s[4:5] nt
	s_add_u32 s4, s4, 0x8000
	s_addc_u32 s5, s5, 0
	global_load_dwordx4 v[56:59], v64, s[4:5] nt
	s_add_u32 s4, s4, 0x8000
	s_addc_u32 s5, s5, 0
	global_load_dwordx4 v[60:63], v64, s[4:5] nt
	s_waitcnt vmcnt(0)
	s_branch .Lcv_wdl_body

.Lcv_wdl_body:
	s_mov_b32 s22, s24
	s_mov_b32 s23, s25
	v_mov_b32_e32 v69, v65
	ds_write2_b32 v69, v0, v1 offset1:1
	ds_write2_b32 v69, v2, v3 offset0:2 offset1:3
	v_add_u32_e32 v69, 0x410, v69
	ds_write2_b32 v69, v4, v5 offset1:1
	ds_write2_b32 v69, v6, v7 offset0:2 offset1:3
	v_add_u32_e32 v69, 0x410, v69
	ds_write2_b32 v69, v8, v9 offset1:1
	ds_write2_b32 v69, v10, v11 offset0:2 offset1:3
	v_add_u32_e32 v69, 0x410, v69
	ds_write2_b32 v69, v12, v13 offset1:1
	ds_write2_b32 v69, v14, v15 offset0:2 offset1:3
	v_add_u32_e32 v69, 0x410, v69
	ds_write2_b32 v69, v16, v17 offset1:1
	ds_write2_b32 v69, v18, v19 offset0:2 offset1:3
	v_add_u32_e32 v69, 0x410, v69
	ds_write2_b32 v69, v20, v21 offset1:1
	ds_write2_b32 v69, v22, v23 offset0:2 offset1:3
	v_add_u32_e32 v69, 0x410, v69
	ds_write2_b32 v69, v24, v25 offset1:1
	ds_write2_b32 v69, v26, v27 offset0:2 offset1:3
	v_add_u32_e32 v69, 0x410, v69
	ds_write2_b32 v69, v28, v29 offset1:1
	ds_write2_b32 v69, v30, v31 offset0:2 offset1:3
	v_add_u32_e32 v69, 0x410, v69
	ds_write2_b32 v69, v32, v33 offset1:1
	ds_write2_b32 v69, v34, v35 offset0:2 offset1:3
	v_add_u32_e32 v69, 0x410, v69
	ds_write2_b32 v69, v36, v37 offset1:1
	ds_write2_b32 v69, v38, v39 offset0:2 offset1:3
	v_add_u32_e32 v69, 0x410, v69
	ds_write2_b32 v69, v40, v41 offset1:1
	ds_write2_b32 v69, v42, v43 offset0:2 offset1:3
	v_add_u32_e32 v69, 0x410, v69
	ds_write2_b32 v69, v44, v45 offset1:1
	ds_write2_b32 v69, v46, v47 offset0:2 offset1:3
	v_add_u32_e32 v69, 0x410, v69
	ds_write2_b32 v69, v48, v49 offset1:1
	ds_write2_b32 v69, v50, v51 offset0:2 offset1:3
	v_add_u32_e32 v69, 0x410, v69
	ds_write2_b32 v69, v52, v53 offset1:1
	ds_write2_b32 v69, v54, v55 offset0:2 offset1:3
	v_add_u32_e32 v69, 0x410, v69
	ds_write2_b32 v69, v56, v57 offset1:1
	ds_write2_b32 v69, v58, v59 offset0:2 offset1:3
	v_add_u32_e32 v69, 0x410, v69
	ds_write2_b32 v69, v60, v61 offset1:1
	ds_write2_b32 v69, v62, v63 offset0:2 offset1:3
	s_waitcnt lgkmcnt(0)
	s_addk_i32 s16, 0x400
	s_cmp_lt_u32 s16, 0xb00
	s_cbranch_scc0 .Lcv_wdl_noload
	s_lshr_b32 s98, s16, 5
	s_and_b32 s99, s16, 31
	s_lshl_b32 s0, s98, 19
	s_lshl_b32 s100, s99, 8
	s_add_u32 s0, s0, s100
	s_add_u32 s4, s18, s0
	s_addc_u32 s5, s19, 0
	s_mul_i32 s0, s99, 0xb0000
	s_lshl_b32 s100, s98, 7
	s_add_u32 s0, s0, s100
	s_add_u32 s24, s26, s0
	s_addc_u32 s25, s27, 0
	global_load_dwordx4 v[0:3], v64, s[4:5] nt
	s_add_u32 s4, s4, 0x8000
	s_addc_u32 s5, s5, 0
	global_load_dwordx4 v[4:7], v64, s[4:5] nt
	s_add_u32 s4, s4, 0x8000
	s_addc_u32 s5, s5, 0
	global_load_dwordx4 v[8:11], v64, s[4:5] nt
	s_add_u32 s4, s4, 0x8000
	s_addc_u32 s5, s5, 0
	global_load_dwordx4 v[12:15], v64, s[4:5] nt
	s_add_u32 s4, s4, 0x8000
	s_addc_u32 s5, s5, 0
	global_load_dwordx4 v[16:19], v64, s[4:5] nt
	s_add_u32 s4, s4, 0x8000
	s_addc_u32 s5, s5, 0
	global_load_dwordx4 v[20:23], v64, s[4:5] nt
	s_add_u32 s4, s4, 0x8000
	s_addc_u32 s5, s5, 0
	global_load_dwordx4 v[24:27], v64, s[4:5] nt
	s_add_u32 s4, s4, 0x8000
	s_addc_u32 s5, s5, 0
	global_load_dwordx4 v[28:31], v64, s[4:5] nt
	s_add_u32 s4, s4, 0x8000
	s_addc_u32 s5, s5, 0
	global_load_dwordx4 v[32:35], v64, s[4:5] nt
	s_add_u32 s4, s4, 0x8000
	s_addc_u32 s5, s5, 0
	global_load_dwordx4 v[36:39], v64, s[4:5] nt
	s_add_u32 s4, s4, 0x8000
	s_addc_u32 s5, s5, 0
	global_load_dwordx4 v[40:43], v64, s[4:5] nt
	s_add_u32 s4, s4, 0x8000
	s_addc_u32 s5, s5, 0
	global_load_dwordx4 v[44:47], v64, s[4:5] nt
	s_add_u32 s4, s4, 0x8000
	s_addc_u32 s5, s5, 0
	global_load_dwordx4 v[48:51], v64, s[4:5] nt
	s_add_u32 s4, s4, 0x8000
	s_addc_u32 s5, s5, 0
	global_load_dwordx4 v[52:55], v64, s[4:5] nt
	s_add_u32 s4, s4, 0x8000
	s_addc_u32 s5, s5, 0
	global_load_dwordx4 v[56:59], v64, s[4:5] nt
	s_add_u32 s4, s4, 0x8000
	s_addc_u32 s5, s5, 0
	global_load_dwordx4 v[60:63], v64, s[4:5] nt
.Lcv_wdl_noload:
	s_mov_b32 s8, s22
	s_mov_b32 s9, s23
	ds_read2_b32 v[70:71], v66 offset0:0 offset1:8
	ds_read2_b32 v[72:73], v66 offset0:65 offset1:73
	ds_read2_b32 v[74:75], v66 offset0:130 offset1:138
	ds_read2_b32 v[76:77], v66 offset0:195 offset1:203
	ds_read2_b32 v[78:79], v67 offset0:0 offset1:8
	ds_read2_b32 v[80:81], v67 offset0:65 offset1:73
	ds_read2_b32 v[82:83], v67 offset0:130 offset1:138
	ds_read2_b32 v[84:85], v67 offset0:195 offset1:203
	ds_read2_b32 v[86:87], v66 offset0:16 offset1:24
	ds_read2_b32 v[88:89], v66 offset0:81 offset1:89
	ds_read2_b32 v[90:91], v66 offset0:146 offset1:154
	ds_read2_b32 v[92:93], v66 offset0:211 offset1:219
	ds_read2_b32 v[94:95], v67 offset0:16 offset1:24
	ds_read2_b32 v[96:97], v67 offset0:81 offset1:89
	ds_read2_b32 v[98:99], v67 offset0:146 offset1:154
	ds_read2_b32 v[100:101], v67 offset0:211 offset1:219
	s_waitcnt lgkmcnt(8)
	v_cvt_pk_bf16_f32 v102, v70, v72
	v_cvt_pk_bf16_f32 v103, v74, v76
	v_cvt_pk_bf16_f32 v104, v78, v80
	v_cvt_pk_bf16_f32 v105, v82, v84
	v_cvt_pk_bf16_f32 v106, v71, v73
	v_cvt_pk_bf16_f32 v107, v75, v77
	v_cvt_pk_bf16_f32 v108, v79, v81
	v_cvt_pk_bf16_f32 v109, v83, v85
	global_store_dwordx4 v68, v[102:105], s[8:9]
	s_add_u32 s8, s8, 0x16000
	s_addc_u32 s9, s9, 0
	global_store_dwordx4 v68, v[106:109], s[8:9]
	s_add_u32 s8, s8, 0x16000
	s_addc_u32 s9, s9, 0
	ds_read2_b32 v[70:71], v66 offset0:32 offset1:40
	ds_read2_b32 v[72:73], v66 offset0:97 offset1:105
	ds_read2_b32 v[74:75], v66 offset0:162 offset1:170
	ds_read2_b32 v[76:77], v66 offset0:227 offset1:235
	ds_read2_b32 v[78:79], v67 offset0:32 offset1:40
	ds_read2_b32 v[80:81], v67 offset0:97 offset1:105
	ds_read2_b32 v[82:83], v67 offset0:162 offset1:170
	ds_read2_b32 v[84:85], v67 offset0:227 offset1:235
	s_waitcnt lgkmcnt(8)
	v_cvt_pk_bf16_f32 v102, v86, v88
	v_cvt_pk_bf16_f32 v103, v90, v92
	v_cvt_pk_bf16_f32 v104, v94, v96
	v_cvt_pk_bf16_f32 v105, v98, v100
	v_cvt_pk_bf16_f32 v106, v87, v89
	v_cvt_pk_bf16_f32 v107, v91, v93
	v_cvt_pk_bf16_f32 v108, v95, v97
	v_cvt_pk_bf16_f32 v109, v99, v101
	global_store_dwordx4 v68, v[102:105], s[8:9]
	s_add_u32 s8, s8, 0x16000
	s_addc_u32 s9, s9, 0
	global_store_dwordx4 v68, v[106:109], s[8:9]
	s_add_u32 s8, s8, 0x16000
	s_addc_u32 s9, s9, 0
	ds_read2_b32 v[86:87], v66 offset0:48 offset1:56
	ds_read2_b32 v[88:89], v66 offset0:113 offset1:121
	ds_read2_b32 v[90:91], v66 offset0:178 offset1:186
	ds_read2_b32 v[92:93], v66 offset0:243 offset1:251
	ds_read2_b32 v[94:95], v67 offset0:48 offset1:56
	ds_read2_b32 v[96:97], v67 offset0:113 offset1:121
	ds_read2_b32 v[98:99], v67 offset0:178 offset1:186
	ds_read2_b32 v[100:101], v67 offset0:243 offset1:251
	s_waitcnt lgkmcnt(8)
	v_cvt_pk_bf16_f32 v102, v70, v72
	v_cvt_pk_bf16_f32 v103, v74, v76
	v_cvt_pk_bf16_f32 v104, v78, v80
	v_cvt_pk_bf16_f32 v105, v82, v84
	v_cvt_pk_bf16_f32 v106, v71, v73
	v_cvt_pk_bf16_f32 v107, v75, v77
	v_cvt_pk_bf16_f32 v108, v79, v81
	v_cvt_pk_bf16_f32 v109, v83, v85
	global_store_dwordx4 v68, v[102:105], s[8:9]
	s_add_u32 s8, s8, 0x16000
	s_addc_u32 s9, s9, 0
	global_store_dwordx4 v68, v[106:109], s[8:9]
	s_add_u32 s8, s8, 0x16000
	s_addc_u32 s9, s9, 0
	s_waitcnt lgkmcnt(0)
	v_cvt_pk_bf16_f32 v102, v86, v88
	v_cvt_pk_bf16_f32 v103, v90, v92
	v_cvt_pk_bf16_f32 v104, v94, v96
	v_cvt_pk_bf16_f32 v105, v98, v100
	v_cvt_pk_bf16_f32 v106, v87, v89
	v_cvt_pk_bf16_f32 v107, v91, v93
	v_cvt_pk_bf16_f32 v108, v95, v97
	v_cvt_pk_bf16_f32 v109, v99, v101
	global_store_dwordx4 v68, v[102:105], s[8:9]
	s_add_u32 s8, s8, 0x16000
	s_addc_u32 s9, s9, 0
	global_store_dwordx4 v68, v[106:109], s[8:9]
	s_cmp_lt_u32 s16, 0xb00
	s_cbranch_scc1 .Lcv_wdl_top

	.amdhsa_kernel _Z9hymba_fwd4Args
		.amdhsa_group_segment_fixed_size 0
		.amdhsa_private_segment_fixed_size 0
		.amdhsa_kernarg_size 400
		.amdhsa_user_sgpr_count 2
		.amdhsa_user_sgpr_dispatch_ptr 0
		.amdhsa_user_sgpr_queue_ptr 0
		.amdhsa_user_sgpr_kernarg_segment_ptr 1
		.amdhsa_user_sgpr_dispatch_id 0
		.amdhsa_user_sgpr_kernarg_preload_length 0
		.amdhsa_user_sgpr_kernarg_preload_offset 0
		.amdhsa_user_sgpr_private_segment_size 0
		.amdhsa_uses_dynamic_stack 0
		.amdhsa_enable_private_segment 0
		.amdhsa_system_sgpr_workgroup_id_x 1
		.amdhsa_system_sgpr_workgroup_id_y 0
		.amdhsa_system_sgpr_workgroup_id_z 0
		.amdhsa_system_sgpr_workgroup_info 0
		.amdhsa_system_vgpr_workitem_id 2
		.amdhsa_next_free_vgpr 256
		.amdhsa_next_free_sgpr 102
		.amdhsa_accum_offset 256
		.amdhsa_reserve_vcc 1
		.amdhsa_float_round_mode_32 0
		.amdhsa_float_round_mode_16_64 0
		.amdhsa_float_denorm_mode_32 3
		.amdhsa_float_denorm_mode_16_64 3
		.amdhsa_dx10_clamp 1
		.amdhsa_ieee_mode 1
		.amdhsa_fp16_overflow 0
		.amdhsa_tg_split 0
		.amdhsa_exception_fp_ieee_invalid_op 0
		.amdhsa_exception_fp_denorm_src 0
		.amdhsa_exception_fp_ieee_div_zero 0
		.amdhsa_exception_fp_ieee_overflow 0
		.amdhsa_exception_fp_ieee_underflow 0
		.amdhsa_exception_fp_ieee_inexact 0
		.amdhsa_exception_int_div_zero 0
	.end_amdhsa_kernel

amdhsa.kernels:
  - .agpr_count:     0
    .args:
      - .offset:         0
        .size:           144
        .value_kind:     by_value
      - .offset:         144
        .size:           4
        .value_kind:     hidden_block_count_x
      - .offset:         148
        .size:           4
        .value_kind:     hidden_block_count_y
      - .offset:         152
        .size:           4
        .value_kind:     hidden_block_count_z
      - .offset:         156
        .size:           2
        .value_kind:     hidden_group_size_x
      - .offset:         158
        .size:           2
        .value_kind:     hidden_group_size_y
      - .offset:         160
        .size:           2
        .value_kind:     hidden_group_size_z
      - .offset:         162
        .size:           2
        .value_kind:     hidden_remainder_x
      - .offset:         164
        .size:           2
        .value_kind:     hidden_remainder_y
      - .offset:         166
        .size:           2
        .value_kind:     hidden_remainder_z
      - .offset:         184
        .size:           8
        .value_kind:     hidden_global_offset_x
      - .offset:         192
        .size:           8
        .value_kind:     hidden_global_offset_y
      - .offset:         200
        .size:           8
        .value_kind:     hidden_global_offset_z
      - .offset:         208
        .size:           2
        .value_kind:     hidden_grid_dims
      - .offset:         232
        .size:           8
        .value_kind:     hidden_multigrid_sync_arg
      - .offset:         264
        .size:           4
        .value_kind:     hidden_dynamic_lds_size
    .group_segment_fixed_size: 0
    .kernarg_segment_align: 8
    .kernarg_segment_size: 400
    .language:       OpenCL C
    .language_version:
      - 2
      - 0
    .max_flat_workgroup_size: 512
    .name:           _Z9hymba_fwd4Args
    .private_segment_fixed_size: 0
    .sgpr_count:     108
    .sgpr_spill_count: 13
    .symbol:         _Z9hymba_fwd4Args.kd
    .uniform_work_group_size: 1
    .uses_dynamic_stack: false
    .vgpr_count:     256
    .vgpr_spill_count: 0
    .wavefront_size: 64
